# all 6 GEMM K-loops: LDS-DMA loads use SGPR-base addressing where possible (per-load 64-bit VALU adds removed: 12/16 per iteration, 8/16 in the FFN-down loop)
# baseline (speedup 1.0000x reference)
.LBB0_216:
	s_add_u32 s28, s50, 0xfff80080
	s_addc_u32 s29, s51, -1
	s_add_i32 s89, 0, 0x10000
	s_cmp_eq_u32 s88, 28
	s_cselect_b32 s53, s43, s29
	s_cselect_b32 s52, s84, s28
	s_cselect_b32 s29, s41, s87
	s_cselect_b32 s28, s85, s86
	s_add_i32 s92, 0, 0x14000
	v_add_u32_e32 v158, s89, v147
	v_add_u32_e32 v174, s92, v147
	ds_read_b128 v[142:145], v158
	ds_read_b128 v[150:153], v158 offset:1024
	ds_read_b128 v[154:157], v158 offset:2048
	ds_read_b128 v[158:161], v158 offset:3072
	ds_read_b128 v[162:165], v174
	ds_read_b128 v[166:169], v174 offset:1024
	ds_read_b128 v[170:173], v174 offset:2048
	ds_read_b128 v[174:177], v174 offset:3072
	s_add_i32 m0, s36, 0xc000
	ds_read_b128 v[178:181], v149
	ds_read_b128 v[182:185], v149 offset:1024
	ds_read_b128 v[186:189], v149 offset:2048
	ds_read_b128 v[190:193], v149 offset:3072
	ds_read_b128 v[194:197], v149 offset:4096
	ds_read_b128 v[198:201], v149 offset:5120
	ds_read_b128 v[202:205], v149 offset:6144
	ds_read_b128 v[224:227], v149 offset:7168
	global_load_lds_dwordx4 v138, s[50:51]
	s_add_i32 m0, s36, 0xe000
	s_nop 0
	global_load_lds_dwordx4 v140, s[50:51]
	s_waitcnt vmcnt(8)
	s_waitcnt lgkmcnt(0)
	s_barrier
	s_setprio 1
	s_waitcnt lgkmcnt(0)
	v_mfma_f32_16x16x32_bf16 v[126:129], v[142:145], v[178:181], v[126:129]
	v_mfma_f32_16x16x32_bf16 v[122:125], v[154:157], v[178:181], v[122:125]
	v_mfma_f32_16x16x32_bf16 v[118:121], v[142:145], v[186:189], v[118:121]
	v_mfma_f32_16x16x32_bf16 v[110:113], v[154:157], v[186:189], v[110:113]
	v_mfma_f32_16x16x32_bf16 v[102:105], v[142:145], v[194:197], v[102:105]
	v_mfma_f32_16x16x32_bf16 v[94:97], v[154:157], v[194:197], v[94:97]
	v_mfma_f32_16x16x32_bf16 v[86:89], v[142:145], v[202:205], v[86:89]
	v_mfma_f32_16x16x32_bf16 v[78:81], v[154:157], v[202:205], v[78:81]
	v_mfma_f32_16x16x32_bf16 v[126:129], v[150:153], v[182:185], v[126:129]
	v_mfma_f32_16x16x32_bf16 v[122:125], v[158:161], v[182:185], v[122:125]
	v_mfma_f32_16x16x32_bf16 v[118:121], v[150:153], v[190:193], v[118:121]
	v_mfma_f32_16x16x32_bf16 v[110:113], v[158:161], v[190:193], v[110:113]
	v_mfma_f32_16x16x32_bf16 v[102:105], v[150:153], v[198:201], v[102:105]
	v_mfma_f32_16x16x32_bf16 v[94:97], v[158:161], v[198:201], v[94:97]
	v_mfma_f32_16x16x32_bf16 v[86:89], v[150:153], v[224:227], v[86:89]
	v_mfma_f32_16x16x32_bf16 v[78:81], v[158:161], v[224:227], v[78:81]
	s_setprio 0
	s_setprio 1
	v_mfma_f32_16x16x32_bf16 v[114:117], v[162:165], v[178:181], v[114:117]
	v_mfma_f32_16x16x32_bf16 v[106:109], v[170:173], v[178:181], v[106:109]
	v_mfma_f32_16x16x32_bf16 v[98:101], v[162:165], v[186:189], v[98:101]
	v_mfma_f32_16x16x32_bf16 v[90:93], v[170:173], v[186:189], v[90:93]
	v_mfma_f32_16x16x32_bf16 v[82:85], v[162:165], v[194:197], v[82:85]
	v_mfma_f32_16x16x32_bf16 v[74:77], v[170:173], v[194:197], v[74:77]
	v_mfma_f32_16x16x32_bf16 v[70:73], v[162:165], v[202:205], v[70:73]
	v_mfma_f32_16x16x32_bf16 v[66:69], v[170:173], v[202:205], v[66:69]
	v_mfma_f32_16x16x32_bf16 v[114:117], v[166:169], v[182:185], v[114:117]
	v_mfma_f32_16x16x32_bf16 v[106:109], v[174:177], v[182:185], v[106:109]
	v_mfma_f32_16x16x32_bf16 v[98:101], v[166:169], v[190:193], v[98:101]
	v_mfma_f32_16x16x32_bf16 v[90:93], v[174:177], v[190:193], v[90:93]
	v_mfma_f32_16x16x32_bf16 v[82:85], v[166:169], v[198:201], v[82:85]
	v_mfma_f32_16x16x32_bf16 v[74:77], v[174:177], v[198:201], v[74:77]
	v_mfma_f32_16x16x32_bf16 v[70:73], v[166:169], v[224:227], v[70:73]
	v_mfma_f32_16x16x32_bf16 v[66:69], v[174:177], v[224:227], v[66:69]
	s_setprio 0
	s_barrier
	s_add_i32 s89, s89, s26
	s_mov_b32 m0, s89
	ds_read_b128 v[178:181], v149 offset:16384
	ds_read_b128 v[182:185], v149 offset:17408
	ds_read_b128 v[186:189], v149 offset:18432
	ds_read_b128 v[190:193], v149 offset:19456
	ds_read_b128 v[194:197], v149 offset:20480
	ds_read_b128 v[198:201], v149 offset:21504
	ds_read_b128 v[202:205], v149 offset:22528
	ds_read_b128 v[224:227], v149 offset:23552
	global_load_lds_dwordx4 v134, s[28:29]
	s_add_i32 m0, s89, 0x2000
	s_add_u32 s90, s28, 0x80000
	s_addc_u32 s91, s29, 0
	s_add_i32 s89, s92, s26
	global_load_lds_dwordx4 v130, s[28:29]
	s_mov_b32 m0, s89
	v_lshl_add_u64 v[232:233], s[52:53], 0, v[132:133]
	global_load_lds_dwordx4 v134, s[90:91]
	s_add_i32 m0, s89, 0x2000
	s_nop 0
	global_load_lds_dwordx4 v130, s[90:91]
	v_lshl_add_u64 v[230:231], s[52:53], 0, v[136:137]
	s_mov_b32 m0, s36
	s_nop 0
	global_load_lds_dwordx4 v[230:231], off
	s_mov_b32 m0, s37
	s_nop 0
	global_load_lds_dwordx4 v[232:233], off
	s_waitcnt vmcnt(8)
	s_waitcnt lgkmcnt(0)
	s_barrier
	s_setprio 1
	s_waitcnt lgkmcnt(0)
	v_mfma_f32_16x16x32_bf16 v[62:65], v[142:145], v[178:181], v[62:65]
	v_mfma_f32_16x16x32_bf16 v[58:61], v[154:157], v[178:181], v[58:61]
	v_mfma_f32_16x16x32_bf16 v[54:57], v[142:145], v[186:189], v[54:57]
	v_mfma_f32_16x16x32_bf16 v[46:49], v[154:157], v[186:189], v[46:49]
	v_mfma_f32_16x16x32_bf16 v[38:41], v[142:145], v[194:197], v[38:41]
	v_mfma_f32_16x16x32_bf16 v[30:33], v[154:157], v[194:197], v[30:33]
	v_mfma_f32_16x16x32_bf16 v[22:25], v[142:145], v[202:205], v[22:25]
	v_mfma_f32_16x16x32_bf16 v[12:15], v[154:157], v[202:205], v[12:15]
	v_mfma_f32_16x16x32_bf16 v[62:65], v[150:153], v[182:185], v[62:65]
	v_mfma_f32_16x16x32_bf16 v[58:61], v[158:161], v[182:185], v[58:61]
	v_mfma_f32_16x16x32_bf16 v[54:57], v[150:153], v[190:193], v[54:57]
	v_mfma_f32_16x16x32_bf16 v[46:49], v[158:161], v[190:193], v[46:49]
	v_mfma_f32_16x16x32_bf16 v[38:41], v[150:153], v[198:201], v[38:41]
	v_mfma_f32_16x16x32_bf16 v[30:33], v[158:161], v[198:201], v[30:33]
	v_mfma_f32_16x16x32_bf16 v[22:25], v[150:153], v[224:227], v[22:25]
	v_mfma_f32_16x16x32_bf16 v[12:15], v[158:161], v[224:227], v[12:15]
	s_setprio 0
	s_setprio 1
	v_mfma_f32_16x16x32_bf16 v[50:53], v[162:165], v[178:181], v[50:53]
	v_mfma_f32_16x16x32_bf16 v[42:45], v[170:173], v[178:181], v[42:45]
	v_mfma_f32_16x16x32_bf16 v[34:37], v[162:165], v[186:189], v[34:37]
	v_mfma_f32_16x16x32_bf16 v[26:29], v[170:173], v[186:189], v[26:29]
	v_mfma_f32_16x16x32_bf16 v[18:21], v[162:165], v[194:197], v[18:21]
	v_mfma_f32_16x16x32_bf16 v[8:11], v[170:173], v[194:197], v[8:11]
	v_mfma_f32_16x16x32_bf16 v[4:7], v[162:165], v[202:205], v[4:7]
	v_mfma_f32_16x16x32_bf16 v[0:3], v[170:173], v[202:205], v[0:3]
	v_mfma_f32_16x16x32_bf16 v[50:53], v[166:169], v[182:185], v[50:53]
	v_mfma_f32_16x16x32_bf16 v[42:45], v[174:177], v[182:185], v[42:45]
	v_mfma_f32_16x16x32_bf16 v[34:37], v[166:169], v[190:193], v[34:37]
	v_mfma_f32_16x16x32_bf16 v[26:29], v[174:177], v[190:193], v[26:29]
	v_mfma_f32_16x16x32_bf16 v[18:21], v[166:169], v[198:201], v[18:21]
	v_mfma_f32_16x16x32_bf16 v[8:11], v[174:177], v[198:201], v[8:11]
	v_mfma_f32_16x16x32_bf16 v[4:7], v[166:169], v[224:227], v[4:7]
	v_mfma_f32_16x16x32_bf16 v[0:3], v[174:177], v[224:227], v[0:3]
	s_setprio 0
	s_barrier
	s_add_i32 s89, 0, 0x18000
	s_add_i32 s90, 0, 0x1c000
	v_add_u32_e32 v158, s89, v147
	v_add_u32_e32 v174, s90, v147
	ds_read_b128 v[142:145], v158
	ds_read_b128 v[150:153], v158 offset:1024
	ds_read_b128 v[154:157], v158 offset:2048
	ds_read_b128 v[158:161], v158 offset:3072
	ds_read_b128 v[162:165], v174
	ds_read_b128 v[166:169], v174 offset:1024
	ds_read_b128 v[170:173], v174 offset:2048
	ds_read_b128 v[174:177], v174 offset:3072
	s_add_u32 s52, s52, 0x80000
	s_addc_u32 s53, s53, 0
	s_mov_b32 m0, s49
	ds_read_b128 v[178:181], v149 offset:32768
	ds_read_b128 v[182:185], v149 offset:33792
	ds_read_b128 v[186:189], v149 offset:34816
	ds_read_b128 v[190:193], v149 offset:35840
	ds_read_b128 v[194:197], v149 offset:36864
	ds_read_b128 v[198:201], v149 offset:37888
	ds_read_b128 v[202:205], v149 offset:38912
	ds_read_b128 v[224:227], v149 offset:39936
	global_load_lds_dwordx4 v136, s[52:53]
	s_mov_b32 m0, s56
	s_nop 0
	global_load_lds_dwordx4 v132, s[52:53]
	s_waitcnt vmcnt(8)
	s_waitcnt lgkmcnt(0)
	s_barrier
	s_setprio 1
	s_waitcnt lgkmcnt(0)
	v_mfma_f32_16x16x32_bf16 v[126:129], v[142:145], v[178:181], v[126:129]
	v_mfma_f32_16x16x32_bf16 v[122:125], v[154:157], v[178:181], v[122:125]
	v_mfma_f32_16x16x32_bf16 v[118:121], v[142:145], v[186:189], v[118:121]
	v_mfma_f32_16x16x32_bf16 v[110:113], v[154:157], v[186:189], v[110:113]
	v_mfma_f32_16x16x32_bf16 v[102:105], v[142:145], v[194:197], v[102:105]
	v_mfma_f32_16x16x32_bf16 v[94:97], v[154:157], v[194:197], v[94:97]
	v_mfma_f32_16x16x32_bf16 v[86:89], v[142:145], v[202:205], v[86:89]
	v_mfma_f32_16x16x32_bf16 v[78:81], v[154:157], v[202:205], v[78:81]
	v_mfma_f32_16x16x32_bf16 v[126:129], v[150:153], v[182:185], v[126:129]
	v_mfma_f32_16x16x32_bf16 v[122:125], v[158:161], v[182:185], v[122:125]
	v_mfma_f32_16x16x32_bf16 v[118:121], v[150:153], v[190:193], v[118:121]
	v_mfma_f32_16x16x32_bf16 v[110:113], v[158:161], v[190:193], v[110:113]
	v_mfma_f32_16x16x32_bf16 v[102:105], v[150:153], v[198:201], v[102:105]
	v_mfma_f32_16x16x32_bf16 v[94:97], v[158:161], v[198:201], v[94:97]
	v_mfma_f32_16x16x32_bf16 v[86:89], v[150:153], v[224:227], v[86:89]
	v_mfma_f32_16x16x32_bf16 v[78:81], v[158:161], v[224:227], v[78:81]
	s_setprio 0
	s_setprio 1
	v_mfma_f32_16x16x32_bf16 v[114:117], v[162:165], v[178:181], v[114:117]
	v_mfma_f32_16x16x32_bf16 v[106:109], v[170:173], v[178:181], v[106:109]
	v_mfma_f32_16x16x32_bf16 v[98:101], v[162:165], v[186:189], v[98:101]
	v_mfma_f32_16x16x32_bf16 v[90:93], v[170:173], v[186:189], v[90:93]
	v_mfma_f32_16x16x32_bf16 v[82:85], v[162:165], v[194:197], v[82:85]
	v_mfma_f32_16x16x32_bf16 v[74:77], v[170:173], v[194:197], v[74:77]
	v_mfma_f32_16x16x32_bf16 v[70:73], v[162:165], v[202:205], v[70:73]
	v_mfma_f32_16x16x32_bf16 v[66:69], v[170:173], v[202:205], v[66:69]
	v_mfma_f32_16x16x32_bf16 v[114:117], v[166:169], v[182:185], v[114:117]
	v_mfma_f32_16x16x32_bf16 v[106:109], v[174:177], v[182:185], v[106:109]
	v_mfma_f32_16x16x32_bf16 v[98:101], v[166:169], v[190:193], v[98:101]
	v_mfma_f32_16x16x32_bf16 v[90:93], v[174:177], v[190:193], v[90:93]
	v_mfma_f32_16x16x32_bf16 v[82:85], v[166:169], v[198:201], v[82:85]
	v_mfma_f32_16x16x32_bf16 v[74:77], v[174:177], v[198:201], v[74:77]
	v_mfma_f32_16x16x32_bf16 v[70:73], v[166:169], v[224:227], v[70:73]
	v_mfma_f32_16x16x32_bf16 v[66:69], v[174:177], v[224:227], v[66:69]
	s_setprio 0
	s_barrier
	s_add_i32 s52, s89, s26
	s_add_u32 s28, s28, 0x80
	s_addc_u32 s29, s29, 0
	s_mov_b32 m0, s52
	ds_read_b128 v[178:181], v149 offset:49152
	ds_read_b128 v[182:185], v149 offset:50176
	ds_read_b128 v[186:189], v149 offset:51200
	ds_read_b128 v[190:193], v149 offset:52224
	ds_read_b128 v[194:197], v149 offset:53248
	ds_read_b128 v[198:201], v149 offset:54272
	ds_read_b128 v[202:205], v149 offset:55296
	ds_read_b128 v[224:227], v149 offset:56320
	global_load_lds_dwordx4 v134, s[28:29]
	s_add_i32 m0, s52, 0x2000
	s_add_i32 s52, s90, s26
	global_load_lds_dwordx4 v130, s[28:29]
	s_add_u32 s28, s28, 0x80000
	s_addc_u32 s29, s29, 0
	s_mov_b32 m0, s52
	s_nop 0
	global_load_lds_dwordx4 v134, s[28:29]
	s_add_i32 m0, s52, 0x2000
	s_nop 0
	global_load_lds_dwordx4 v130, s[28:29]
	v_lshl_add_u64 v[206:207], v[230:231], 0, s[34:35]
	s_mov_b32 m0, s57
	s_nop 0
	global_load_lds_dwordx4 v[206:207], off
	v_lshl_add_u64 v[206:207], v[232:233], 0, s[34:35]
	s_mov_b32 m0, s58
	s_nop 0
	global_load_lds_dwordx4 v[206:207], off
	s_waitcnt vmcnt(8)
	s_waitcnt lgkmcnt(0)
	s_barrier
	s_setprio 1
	s_waitcnt lgkmcnt(0)
	v_mfma_f32_16x16x32_bf16 v[62:65], v[142:145], v[178:181], v[62:65]
	v_mfma_f32_16x16x32_bf16 v[58:61], v[154:157], v[178:181], v[58:61]
	v_mfma_f32_16x16x32_bf16 v[54:57], v[142:145], v[186:189], v[54:57]
	v_mfma_f32_16x16x32_bf16 v[46:49], v[154:157], v[186:189], v[46:49]
	v_mfma_f32_16x16x32_bf16 v[38:41], v[142:145], v[194:197], v[38:41]
	v_mfma_f32_16x16x32_bf16 v[30:33], v[154:157], v[194:197], v[30:33]
	v_mfma_f32_16x16x32_bf16 v[22:25], v[142:145], v[202:205], v[22:25]
	v_mfma_f32_16x16x32_bf16 v[12:15], v[154:157], v[202:205], v[12:15]
	v_mfma_f32_16x16x32_bf16 v[62:65], v[150:153], v[182:185], v[62:65]
	v_mfma_f32_16x16x32_bf16 v[58:61], v[158:161], v[182:185], v[58:61]
	v_mfma_f32_16x16x32_bf16 v[54:57], v[150:153], v[190:193], v[54:57]
	v_mfma_f32_16x16x32_bf16 v[46:49], v[158:161], v[190:193], v[46:49]
	v_mfma_f32_16x16x32_bf16 v[38:41], v[150:153], v[198:201], v[38:41]
	v_mfma_f32_16x16x32_bf16 v[30:33], v[158:161], v[198:201], v[30:33]
	v_mfma_f32_16x16x32_bf16 v[22:25], v[150:153], v[224:227], v[22:25]
	v_mfma_f32_16x16x32_bf16 v[12:15], v[158:161], v[224:227], v[12:15]
	s_setprio 0
	s_setprio 1
	v_mfma_f32_16x16x32_bf16 v[50:53], v[162:165], v[178:181], v[50:53]
	v_mfma_f32_16x16x32_bf16 v[42:45], v[170:173], v[178:181], v[42:45]
	v_mfma_f32_16x16x32_bf16 v[34:37], v[162:165], v[186:189], v[34:37]
	v_mfma_f32_16x16x32_bf16 v[26:29], v[170:173], v[186:189], v[26:29]
	v_mfma_f32_16x16x32_bf16 v[18:21], v[162:165], v[194:197], v[18:21]
	v_mfma_f32_16x16x32_bf16 v[8:11], v[170:173], v[194:197], v[8:11]
	v_mfma_f32_16x16x32_bf16 v[4:7], v[162:165], v[202:205], v[4:7]
	v_mfma_f32_16x16x32_bf16 v[0:3], v[170:173], v[202:205], v[0:3]
	v_mfma_f32_16x16x32_bf16 v[50:53], v[166:169], v[182:185], v[50:53]
	v_mfma_f32_16x16x32_bf16 v[42:45], v[174:177], v[182:185], v[42:45]
	v_mfma_f32_16x16x32_bf16 v[34:37], v[166:169], v[190:193], v[34:37]
	v_mfma_f32_16x16x32_bf16 v[26:29], v[174:177], v[190:193], v[26:29]
	v_mfma_f32_16x16x32_bf16 v[18:21], v[166:169], v[198:201], v[18:21]
	v_mfma_f32_16x16x32_bf16 v[8:11], v[174:177], v[198:201], v[8:11]
	v_mfma_f32_16x16x32_bf16 v[4:7], v[166:169], v[224:227], v[4:7]
	v_mfma_f32_16x16x32_bf16 v[0:3], v[174:177], v[224:227], v[0:3]
	s_setprio 0
	s_barrier
	s_add_i32 s88, s88, 2
	s_add_u32 s50, s50, 0x100
	s_addc_u32 s51, s51, 0
	s_add_u32 s86, s86, 0x100
	s_addc_u32 s87, s87, 0
	s_cmp_gt_u32 s88, 29
	s_cbranch_scc0 .LBB0_216
	s_and_b64 vcc, exec, s[18:19]
	s_cbranch_vccz .LBB0_221
	s_barrier
	s_cmp_gt_i32 s83, 13
	s_mov_b64 s[28:29], -1
	s_cbranch_scc1 .LBB0_222

.LBB0_649:
	s_add_u32 s28, s40, 0xfff80080
	s_addc_u32 s29, s41, -1
	s_add_i32 s88, 0, 0x10000
	s_cmp_eq_u32 s87, 4
	s_cselect_b32 s47, s27, s29
	s_cselect_b32 s46, s26, s28
	v_add_u32_e32 v140, s88, v143
	s_cselect_b32 s29, s19, s49
	s_cselect_b32 s28, s23, s48
	s_add_i32 s90, 0, 0x14000
	ds_read_b128 v[146:149], v140
	ds_read_b128 v[150:153], v140 offset:1024
	ds_read_b128 v[154:157], v140 offset:2048
	ds_read_b128 v[158:161], v140 offset:3072
	v_add_u32_e32 v140, s90, v143
	ds_read_b128 v[162:165], v140
	ds_read_b128 v[166:169], v140 offset:1024
	ds_read_b128 v[170:173], v140 offset:2048
	ds_read_b128 v[174:177], v140 offset:3072
	s_add_i32 m0, s45, 0xc000
	ds_read_b128 v[178:181], v145
	ds_read_b128 v[182:185], v145 offset:1024
	ds_read_b128 v[186:189], v145 offset:2048
	ds_read_b128 v[190:193], v145 offset:3072
	ds_read_b128 v[194:197], v145 offset:4096
	ds_read_b128 v[198:201], v145 offset:5120
	ds_read_b128 v[202:205], v145 offset:6144
	ds_read_b128 v[224:227], v145 offset:7168
	global_load_lds_dwordx4 v136, s[40:41]
	s_add_i32 m0, s45, 0xe000
	s_nop 0
	global_load_lds_dwordx4 v138, s[40:41]
	s_waitcnt vmcnt(8)
	s_waitcnt lgkmcnt(0)
	s_barrier
	s_setprio 1
	s_waitcnt lgkmcnt(0)
	v_mfma_f32_16x16x32_bf16 v[126:129], v[146:149], v[178:181], v[126:129]
	v_mfma_f32_16x16x32_bf16 v[122:125], v[154:157], v[178:181], v[122:125]
	v_mfma_f32_16x16x32_bf16 v[118:121], v[146:149], v[186:189], v[118:121]
	v_mfma_f32_16x16x32_bf16 v[110:113], v[154:157], v[186:189], v[110:113]
	v_mfma_f32_16x16x32_bf16 v[102:105], v[146:149], v[194:197], v[102:105]
	v_mfma_f32_16x16x32_bf16 v[94:97], v[154:157], v[194:197], v[94:97]
	v_mfma_f32_16x16x32_bf16 v[86:89], v[146:149], v[202:205], v[86:89]
	v_mfma_f32_16x16x32_bf16 v[78:81], v[154:157], v[202:205], v[78:81]
	v_mfma_f32_16x16x32_bf16 v[126:129], v[150:153], v[182:185], v[126:129]
	v_mfma_f32_16x16x32_bf16 v[122:125], v[158:161], v[182:185], v[122:125]
	v_mfma_f32_16x16x32_bf16 v[118:121], v[150:153], v[190:193], v[118:121]
	v_mfma_f32_16x16x32_bf16 v[110:113], v[158:161], v[190:193], v[110:113]
	v_mfma_f32_16x16x32_bf16 v[102:105], v[150:153], v[198:201], v[102:105]
	v_mfma_f32_16x16x32_bf16 v[94:97], v[158:161], v[198:201], v[94:97]
	v_mfma_f32_16x16x32_bf16 v[86:89], v[150:153], v[224:227], v[86:89]
	v_mfma_f32_16x16x32_bf16 v[78:81], v[158:161], v[224:227], v[78:81]
	s_setprio 0
	s_setprio 1
	v_mfma_f32_16x16x32_bf16 v[114:117], v[162:165], v[178:181], v[114:117]
	v_mfma_f32_16x16x32_bf16 v[106:109], v[170:173], v[178:181], v[106:109]
	v_mfma_f32_16x16x32_bf16 v[98:101], v[162:165], v[186:189], v[98:101]
	v_mfma_f32_16x16x32_bf16 v[90:93], v[170:173], v[186:189], v[90:93]
	v_mfma_f32_16x16x32_bf16 v[82:85], v[162:165], v[194:197], v[82:85]
	v_mfma_f32_16x16x32_bf16 v[74:77], v[170:173], v[194:197], v[74:77]
	v_mfma_f32_16x16x32_bf16 v[70:73], v[162:165], v[202:205], v[70:73]
	v_mfma_f32_16x16x32_bf16 v[66:69], v[170:173], v[202:205], v[66:69]
	v_mfma_f32_16x16x32_bf16 v[114:117], v[166:169], v[182:185], v[114:117]
	v_mfma_f32_16x16x32_bf16 v[106:109], v[174:177], v[182:185], v[106:109]
	v_mfma_f32_16x16x32_bf16 v[98:101], v[166:169], v[190:193], v[98:101]
	v_mfma_f32_16x16x32_bf16 v[90:93], v[174:177], v[190:193], v[90:93]
	v_mfma_f32_16x16x32_bf16 v[82:85], v[166:169], v[198:201], v[82:85]
	v_mfma_f32_16x16x32_bf16 v[74:77], v[174:177], v[198:201], v[74:77]
	v_mfma_f32_16x16x32_bf16 v[70:73], v[166:169], v[224:227], v[70:73]
	v_mfma_f32_16x16x32_bf16 v[66:69], v[174:177], v[224:227], v[66:69]
	s_setprio 0
	s_barrier
	s_add_i32 s88, s88, s37
	s_mov_b32 m0, s88
	ds_read_b128 v[178:181], v145 offset:16384
	ds_read_b128 v[182:185], v145 offset:17408
	ds_read_b128 v[186:189], v145 offset:18432
	ds_read_b128 v[190:193], v145 offset:19456
	ds_read_b128 v[194:197], v145 offset:20480
	ds_read_b128 v[198:201], v145 offset:21504
	ds_read_b128 v[202:205], v145 offset:22528
	ds_read_b128 v[224:227], v145 offset:23552
	global_load_lds_dwordx4 v16, s[28:29]
	s_add_i32 m0, s88, 0x2000
	s_add_u32 s88, s28, 0x20000
	s_addc_u32 s89, s29, 0
	s_add_i32 s90, s90, s37
	global_load_lds_dwordx4 v130, s[28:29]
	s_mov_b32 m0, s90
	v_lshl_add_u64 v[230:231], s[46:47], 0, v[132:133]
	global_load_lds_dwordx4 v16, s[88:89]
	s_add_i32 m0, s90, 0x2000
	s_nop 0
	global_load_lds_dwordx4 v130, s[88:89]
	v_lshl_add_u64 v[228:229], s[46:47], 0, v[134:135]
	s_mov_b32 m0, s45
	s_nop 0
	global_load_lds_dwordx4 v[228:229], off
	s_mov_b32 m0, s53
	s_nop 0
	global_load_lds_dwordx4 v[230:231], off
	s_waitcnt vmcnt(8)
	s_waitcnt lgkmcnt(0)
	s_barrier
	s_setprio 1
	s_waitcnt lgkmcnt(0)
	v_mfma_f32_16x16x32_bf16 v[62:65], v[146:149], v[178:181], v[62:65]
	v_mfma_f32_16x16x32_bf16 v[58:61], v[154:157], v[178:181], v[58:61]
	v_mfma_f32_16x16x32_bf16 v[54:57], v[146:149], v[186:189], v[54:57]
	v_mfma_f32_16x16x32_bf16 v[46:49], v[154:157], v[186:189], v[46:49]
	v_mfma_f32_16x16x32_bf16 v[38:41], v[146:149], v[194:197], v[38:41]
	v_mfma_f32_16x16x32_bf16 v[30:33], v[154:157], v[194:197], v[30:33]
	v_mfma_f32_16x16x32_bf16 v[22:25], v[146:149], v[202:205], v[22:25]
	v_mfma_f32_16x16x32_bf16 v[12:15], v[154:157], v[202:205], v[12:15]
	v_mfma_f32_16x16x32_bf16 v[62:65], v[150:153], v[182:185], v[62:65]
	v_mfma_f32_16x16x32_bf16 v[58:61], v[158:161], v[182:185], v[58:61]
	v_mfma_f32_16x16x32_bf16 v[54:57], v[150:153], v[190:193], v[54:57]
	v_mfma_f32_16x16x32_bf16 v[46:49], v[158:161], v[190:193], v[46:49]
	v_mfma_f32_16x16x32_bf16 v[38:41], v[150:153], v[198:201], v[38:41]
	v_mfma_f32_16x16x32_bf16 v[30:33], v[158:161], v[198:201], v[30:33]
	v_mfma_f32_16x16x32_bf16 v[22:25], v[150:153], v[224:227], v[22:25]
	v_mfma_f32_16x16x32_bf16 v[12:15], v[158:161], v[224:227], v[12:15]
	s_setprio 0
	s_setprio 1
	v_mfma_f32_16x16x32_bf16 v[50:53], v[162:165], v[178:181], v[50:53]
	v_mfma_f32_16x16x32_bf16 v[42:45], v[170:173], v[178:181], v[42:45]
	v_mfma_f32_16x16x32_bf16 v[34:37], v[162:165], v[186:189], v[34:37]
	v_mfma_f32_16x16x32_bf16 v[26:29], v[170:173], v[186:189], v[26:29]
	v_mfma_f32_16x16x32_bf16 v[18:21], v[162:165], v[194:197], v[18:21]
	v_mfma_f32_16x16x32_bf16 v[8:11], v[170:173], v[194:197], v[8:11]
	v_mfma_f32_16x16x32_bf16 v[4:7], v[162:165], v[202:205], v[4:7]
	v_mfma_f32_16x16x32_bf16 v[0:3], v[170:173], v[202:205], v[0:3]
	v_mfma_f32_16x16x32_bf16 v[50:53], v[166:169], v[182:185], v[50:53]
	v_mfma_f32_16x16x32_bf16 v[42:45], v[174:177], v[182:185], v[42:45]
	v_mfma_f32_16x16x32_bf16 v[34:37], v[166:169], v[190:193], v[34:37]
	v_mfma_f32_16x16x32_bf16 v[26:29], v[174:177], v[190:193], v[26:29]
	v_mfma_f32_16x16x32_bf16 v[18:21], v[166:169], v[198:201], v[18:21]
	v_mfma_f32_16x16x32_bf16 v[8:11], v[174:177], v[198:201], v[8:11]
	v_mfma_f32_16x16x32_bf16 v[4:7], v[166:169], v[224:227], v[4:7]
	v_mfma_f32_16x16x32_bf16 v[0:3], v[174:177], v[224:227], v[0:3]
	s_setprio 0
	s_barrier
	s_add_i32 s88, 0, 0x18000
	s_add_i32 s89, 0, 0x1c000
	v_add_u32_e32 v158, s88, v143
	v_add_u32_e32 v174, s89, v143
	ds_read_b128 v[146:149], v158
	ds_read_b128 v[150:153], v158 offset:1024
	ds_read_b128 v[154:157], v158 offset:2048
	ds_read_b128 v[158:161], v158 offset:3072
	ds_read_b128 v[162:165], v174
	ds_read_b128 v[166:169], v174 offset:1024
	ds_read_b128 v[170:173], v174 offset:2048
	ds_read_b128 v[174:177], v174 offset:3072
	s_add_u32 s46, s46, 0x80000
	s_addc_u32 s47, s47, 0
	s_mov_b32 m0, s58
	ds_read_b128 v[178:181], v145 offset:32768
	ds_read_b128 v[182:185], v145 offset:33792
	ds_read_b128 v[186:189], v145 offset:34816
	ds_read_b128 v[190:193], v145 offset:35840
	ds_read_b128 v[194:197], v145 offset:36864
	ds_read_b128 v[198:201], v145 offset:37888
	ds_read_b128 v[202:205], v145 offset:38912
	ds_read_b128 v[224:227], v145 offset:39936
	global_load_lds_dwordx4 v134, s[46:47]
	s_mov_b32 m0, s59
	s_nop 0
	global_load_lds_dwordx4 v132, s[46:47]
	s_waitcnt vmcnt(8)
	s_waitcnt lgkmcnt(0)
	s_barrier
	s_setprio 1
	s_waitcnt lgkmcnt(0)
	v_mfma_f32_16x16x32_bf16 v[126:129], v[146:149], v[178:181], v[126:129]
	v_mfma_f32_16x16x32_bf16 v[122:125], v[154:157], v[178:181], v[122:125]
	v_mfma_f32_16x16x32_bf16 v[118:121], v[146:149], v[186:189], v[118:121]
	v_mfma_f32_16x16x32_bf16 v[110:113], v[154:157], v[186:189], v[110:113]
	v_mfma_f32_16x16x32_bf16 v[102:105], v[146:149], v[194:197], v[102:105]
	v_mfma_f32_16x16x32_bf16 v[94:97], v[154:157], v[194:197], v[94:97]
	v_mfma_f32_16x16x32_bf16 v[86:89], v[146:149], v[202:205], v[86:89]
	v_mfma_f32_16x16x32_bf16 v[78:81], v[154:157], v[202:205], v[78:81]
	v_mfma_f32_16x16x32_bf16 v[126:129], v[150:153], v[182:185], v[126:129]
	v_mfma_f32_16x16x32_bf16 v[122:125], v[158:161], v[182:185], v[122:125]
	v_mfma_f32_16x16x32_bf16 v[118:121], v[150:153], v[190:193], v[118:121]
	v_mfma_f32_16x16x32_bf16 v[110:113], v[158:161], v[190:193], v[110:113]
	v_mfma_f32_16x16x32_bf16 v[102:105], v[150:153], v[198:201], v[102:105]
	v_mfma_f32_16x16x32_bf16 v[94:97], v[158:161], v[198:201], v[94:97]
	v_mfma_f32_16x16x32_bf16 v[86:89], v[150:153], v[224:227], v[86:89]
	v_mfma_f32_16x16x32_bf16 v[78:81], v[158:161], v[224:227], v[78:81]
	s_setprio 0
	s_setprio 1
	v_mfma_f32_16x16x32_bf16 v[114:117], v[162:165], v[178:181], v[114:117]
	v_mfma_f32_16x16x32_bf16 v[106:109], v[170:173], v[178:181], v[106:109]
	v_mfma_f32_16x16x32_bf16 v[98:101], v[162:165], v[186:189], v[98:101]
	v_mfma_f32_16x16x32_bf16 v[90:93], v[170:173], v[186:189], v[90:93]
	v_mfma_f32_16x16x32_bf16 v[82:85], v[162:165], v[194:197], v[82:85]
	v_mfma_f32_16x16x32_bf16 v[74:77], v[170:173], v[194:197], v[74:77]
	v_mfma_f32_16x16x32_bf16 v[70:73], v[162:165], v[202:205], v[70:73]
	v_mfma_f32_16x16x32_bf16 v[66:69], v[170:173], v[202:205], v[66:69]
	v_mfma_f32_16x16x32_bf16 v[114:117], v[166:169], v[182:185], v[114:117]
	v_mfma_f32_16x16x32_bf16 v[106:109], v[174:177], v[182:185], v[106:109]
	v_mfma_f32_16x16x32_bf16 v[98:101], v[166:169], v[190:193], v[98:101]
	v_mfma_f32_16x16x32_bf16 v[90:93], v[174:177], v[190:193], v[90:93]
	v_mfma_f32_16x16x32_bf16 v[82:85], v[166:169], v[198:201], v[82:85]
	v_mfma_f32_16x16x32_bf16 v[74:77], v[174:177], v[198:201], v[74:77]
	v_mfma_f32_16x16x32_bf16 v[70:73], v[166:169], v[224:227], v[70:73]
	v_mfma_f32_16x16x32_bf16 v[66:69], v[174:177], v[224:227], v[66:69]
	s_setprio 0
	s_barrier
	s_add_i32 s46, s88, s37
	s_add_u32 s28, s28, 0x80
	s_addc_u32 s29, s29, 0
	s_mov_b32 m0, s46
	ds_read_b128 v[178:181], v145 offset:49152
	ds_read_b128 v[182:185], v145 offset:50176
	ds_read_b128 v[186:189], v145 offset:51200
	ds_read_b128 v[190:193], v145 offset:52224
	ds_read_b128 v[194:197], v145 offset:53248
	ds_read_b128 v[198:201], v145 offset:54272
	ds_read_b128 v[202:205], v145 offset:55296
	ds_read_b128 v[224:227], v145 offset:56320
	global_load_lds_dwordx4 v16, s[28:29]
	s_add_i32 m0, s46, 0x2000
	s_add_i32 s46, s89, s37
	global_load_lds_dwordx4 v130, s[28:29]
	s_add_u32 s28, s28, 0x20000
	s_addc_u32 s29, s29, 0
	s_mov_b32 m0, s46
	s_nop 0
	global_load_lds_dwordx4 v16, s[28:29]
	s_add_i32 m0, s46, 0x2000
	s_nop 0
	global_load_lds_dwordx4 v130, s[28:29]
	v_lshl_add_u64 v[140:141], v[228:229], 0, s[34:35]
	s_mov_b32 m0, s83
	s_nop 0
	global_load_lds_dwordx4 v[140:141], off
	v_lshl_add_u64 v[140:141], v[230:231], 0, s[34:35]
	s_mov_b32 m0, s84
	s_nop 0
	global_load_lds_dwordx4 v[140:141], off
	s_waitcnt vmcnt(8)
	s_waitcnt lgkmcnt(0)
	s_barrier
	s_setprio 1
	s_waitcnt lgkmcnt(0)
	v_mfma_f32_16x16x32_bf16 v[62:65], v[146:149], v[178:181], v[62:65]
	v_mfma_f32_16x16x32_bf16 v[58:61], v[154:157], v[178:181], v[58:61]
	v_mfma_f32_16x16x32_bf16 v[54:57], v[146:149], v[186:189], v[54:57]
	v_mfma_f32_16x16x32_bf16 v[46:49], v[154:157], v[186:189], v[46:49]
	v_mfma_f32_16x16x32_bf16 v[38:41], v[146:149], v[194:197], v[38:41]
	v_mfma_f32_16x16x32_bf16 v[30:33], v[154:157], v[194:197], v[30:33]
	v_mfma_f32_16x16x32_bf16 v[22:25], v[146:149], v[202:205], v[22:25]
	v_mfma_f32_16x16x32_bf16 v[12:15], v[154:157], v[202:205], v[12:15]
	v_mfma_f32_16x16x32_bf16 v[62:65], v[150:153], v[182:185], v[62:65]
	v_mfma_f32_16x16x32_bf16 v[58:61], v[158:161], v[182:185], v[58:61]
	v_mfma_f32_16x16x32_bf16 v[54:57], v[150:153], v[190:193], v[54:57]
	v_mfma_f32_16x16x32_bf16 v[46:49], v[158:161], v[190:193], v[46:49]
	v_mfma_f32_16x16x32_bf16 v[38:41], v[150:153], v[198:201], v[38:41]
	v_mfma_f32_16x16x32_bf16 v[30:33], v[158:161], v[198:201], v[30:33]
	v_mfma_f32_16x16x32_bf16 v[22:25], v[150:153], v[224:227], v[22:25]
	v_mfma_f32_16x16x32_bf16 v[12:15], v[158:161], v[224:227], v[12:15]
	s_setprio 0
	s_setprio 1
	v_mfma_f32_16x16x32_bf16 v[50:53], v[162:165], v[178:181], v[50:53]
	v_mfma_f32_16x16x32_bf16 v[42:45], v[170:173], v[178:181], v[42:45]
	v_mfma_f32_16x16x32_bf16 v[34:37], v[162:165], v[186:189], v[34:37]
	v_mfma_f32_16x16x32_bf16 v[26:29], v[170:173], v[186:189], v[26:29]
	v_mfma_f32_16x16x32_bf16 v[18:21], v[162:165], v[194:197], v[18:21]
	v_mfma_f32_16x16x32_bf16 v[8:11], v[170:173], v[194:197], v[8:11]
	v_mfma_f32_16x16x32_bf16 v[4:7], v[162:165], v[202:205], v[4:7]
	v_mfma_f32_16x16x32_bf16 v[0:3], v[170:173], v[202:205], v[0:3]
	v_mfma_f32_16x16x32_bf16 v[50:53], v[166:169], v[182:185], v[50:53]
	v_mfma_f32_16x16x32_bf16 v[42:45], v[174:177], v[182:185], v[42:45]
	v_mfma_f32_16x16x32_bf16 v[34:37], v[166:169], v[190:193], v[34:37]
	v_mfma_f32_16x16x32_bf16 v[26:29], v[174:177], v[190:193], v[26:29]
	v_mfma_f32_16x16x32_bf16 v[18:21], v[166:169], v[198:201], v[18:21]
	v_mfma_f32_16x16x32_bf16 v[8:11], v[174:177], v[198:201], v[8:11]
	v_mfma_f32_16x16x32_bf16 v[4:7], v[166:169], v[224:227], v[4:7]
	v_mfma_f32_16x16x32_bf16 v[0:3], v[174:177], v[224:227], v[0:3]
	s_setprio 0
	s_barrier
	s_add_i32 s87, s87, 2
	s_add_u32 s40, s40, 0x100
	s_addc_u32 s41, s41, 0
	s_add_u32 s48, s48, 0x100
	s_addc_u32 s49, s49, 0
	s_cmp_gt_u32 s87, 5
	s_cbranch_scc0 .LBB0_649
	s_and_b64 vcc, exec, s[14:15]
	s_cbranch_vccz .LBB0_652
	s_barrier

.LBB0_717:
	s_add_u32 s28, s44, 0xfff80080
	s_addc_u32 s29, s45, -1
	s_add_i32 s89, 0, 0x10000
	s_cmp_eq_u32 s88, 28
	s_cselect_b32 s47, s23, s29
	s_cselect_b32 s46, s84, s28
	s_cselect_b32 s29, s19, s87
	s_cselect_b32 s28, s85, s86
	s_add_i32 s92, 0, 0x14000
	v_add_u32_e32 v148, s89, v224
	v_add_u32_e32 v164, s92, v224
	ds_read_b128 v[136:139], v148
	ds_read_b128 v[140:143], v148 offset:1024
	ds_read_b128 v[144:147], v148 offset:2048
	ds_read_b128 v[148:151], v148 offset:3072
	ds_read_b128 v[152:155], v164
	ds_read_b128 v[156:159], v164 offset:1024
	ds_read_b128 v[160:163], v164 offset:2048
	ds_read_b128 v[164:167], v164 offset:3072
	s_add_i32 m0, s43, 0xc000
	ds_read_b128 v[168:171], v226
	ds_read_b128 v[172:175], v226 offset:1024
	ds_read_b128 v[176:179], v226 offset:2048
	ds_read_b128 v[180:183], v226 offset:3072
	ds_read_b128 v[184:187], v226 offset:4096
	ds_read_b128 v[188:191], v226 offset:5120
	ds_read_b128 v[192:195], v226 offset:6144
	ds_read_b128 v[196:199], v226 offset:7168
	global_load_lds_dwordx4 v132, s[44:45]
	s_add_i32 m0, s43, 0xe000
	s_nop 0
	global_load_lds_dwordx4 v134, s[44:45]
	s_waitcnt vmcnt(8)
	s_waitcnt lgkmcnt(0)
	s_barrier
	s_setprio 1
	s_waitcnt lgkmcnt(0)
	v_mfma_f32_16x16x32_bf16 v[126:129], v[136:139], v[168:171], v[126:129]
	v_mfma_f32_16x16x32_bf16 v[122:125], v[144:147], v[168:171], v[122:125]
	v_mfma_f32_16x16x32_bf16 v[118:121], v[136:139], v[176:179], v[118:121]
	v_mfma_f32_16x16x32_bf16 v[114:117], v[144:147], v[176:179], v[114:117]
	v_mfma_f32_16x16x32_bf16 v[110:113], v[136:139], v[184:187], v[110:113]
	v_mfma_f32_16x16x32_bf16 v[106:109], v[144:147], v[184:187], v[106:109]
	v_mfma_f32_16x16x32_bf16 v[102:105], v[136:139], v[192:195], v[102:105]
	v_mfma_f32_16x16x32_bf16 v[98:101], v[144:147], v[192:195], v[98:101]
	v_mfma_f32_16x16x32_bf16 v[126:129], v[140:143], v[172:175], v[126:129]
	v_mfma_f32_16x16x32_bf16 v[122:125], v[148:151], v[172:175], v[122:125]
	v_mfma_f32_16x16x32_bf16 v[118:121], v[140:143], v[180:183], v[118:121]
	v_mfma_f32_16x16x32_bf16 v[114:117], v[148:151], v[180:183], v[114:117]
	v_mfma_f32_16x16x32_bf16 v[110:113], v[140:143], v[188:191], v[110:113]
	v_mfma_f32_16x16x32_bf16 v[106:109], v[148:151], v[188:191], v[106:109]
	v_mfma_f32_16x16x32_bf16 v[102:105], v[140:143], v[196:199], v[102:105]
	v_mfma_f32_16x16x32_bf16 v[98:101], v[148:151], v[196:199], v[98:101]
	s_setprio 0
	s_setprio 1
	v_mfma_f32_16x16x32_bf16 v[94:97], v[152:155], v[168:171], v[94:97]
	v_mfma_f32_16x16x32_bf16 v[90:93], v[160:163], v[168:171], v[90:93]
	v_mfma_f32_16x16x32_bf16 v[86:89], v[152:155], v[176:179], v[86:89]
	v_mfma_f32_16x16x32_bf16 v[82:85], v[160:163], v[176:179], v[82:85]
	v_mfma_f32_16x16x32_bf16 v[78:81], v[152:155], v[184:187], v[78:81]
	v_mfma_f32_16x16x32_bf16 v[74:77], v[160:163], v[184:187], v[74:77]
	v_mfma_f32_16x16x32_bf16 v[70:73], v[152:155], v[192:195], v[70:73]
	v_mfma_f32_16x16x32_bf16 v[66:69], v[160:163], v[192:195], v[66:69]
	v_mfma_f32_16x16x32_bf16 v[94:97], v[156:159], v[172:175], v[94:97]
	v_mfma_f32_16x16x32_bf16 v[90:93], v[164:167], v[172:175], v[90:93]
	v_mfma_f32_16x16x32_bf16 v[86:89], v[156:159], v[180:183], v[86:89]
	v_mfma_f32_16x16x32_bf16 v[82:85], v[164:167], v[180:183], v[82:85]
	v_mfma_f32_16x16x32_bf16 v[78:81], v[156:159], v[188:191], v[78:81]
	v_mfma_f32_16x16x32_bf16 v[74:77], v[164:167], v[188:191], v[74:77]
	v_mfma_f32_16x16x32_bf16 v[70:73], v[156:159], v[196:199], v[70:73]
	v_mfma_f32_16x16x32_bf16 v[66:69], v[164:167], v[196:199], v[66:69]
	s_setprio 0
	s_barrier
	s_add_i32 s89, s89, s37
	s_mov_b32 m0, s89
	ds_read_b128 v[168:171], v226 offset:16384
	ds_read_b128 v[172:175], v226 offset:17408
	ds_read_b128 v[176:179], v226 offset:18432
	ds_read_b128 v[180:183], v226 offset:19456
	ds_read_b128 v[184:187], v226 offset:20480
	ds_read_b128 v[188:191], v226 offset:21504
	ds_read_b128 v[192:195], v226 offset:22528
	ds_read_b128 v[196:199], v226 offset:23552
	global_load_lds_dwordx4 v16, s[28:29]
	s_add_i32 m0, s89, 0x2000
	s_add_u32 s90, s28, 0x80000
	s_addc_u32 s91, s29, 0
	s_add_i32 s89, s92, s37
	global_load_lds_dwordx4 v130, s[28:29]
	s_mov_b32 m0, s89
	v_lshl_add_u64 v[206:207], s[46:47], 0, v[130:131]
	global_load_lds_dwordx4 v16, s[90:91]
	s_add_i32 m0, s89, 0x2000
	s_nop 0
	global_load_lds_dwordx4 v130, s[90:91]
	v_lshl_add_u64 v[204:205], s[46:47], 0, v[16:17]
	s_mov_b32 m0, s43
	s_nop 0
	global_load_lds_dwordx4 v[204:205], off
	s_mov_b32 m0, s50
	s_nop 0
	global_load_lds_dwordx4 v[206:207], off
	s_waitcnt vmcnt(8)
	s_waitcnt lgkmcnt(0)
	s_barrier
	s_setprio 1
	s_waitcnt lgkmcnt(0)
	v_mfma_f32_16x16x32_bf16 v[62:65], v[136:139], v[168:171], v[62:65]
	v_mfma_f32_16x16x32_bf16 v[58:61], v[144:147], v[168:171], v[58:61]
	v_mfma_f32_16x16x32_bf16 v[54:57], v[136:139], v[176:179], v[54:57]
	v_mfma_f32_16x16x32_bf16 v[50:53], v[144:147], v[176:179], v[50:53]
	v_mfma_f32_16x16x32_bf16 v[46:49], v[136:139], v[184:187], v[46:49]
	v_mfma_f32_16x16x32_bf16 v[42:45], v[144:147], v[184:187], v[42:45]
	v_mfma_f32_16x16x32_bf16 v[38:41], v[136:139], v[192:195], v[38:41]
	v_mfma_f32_16x16x32_bf16 v[34:37], v[144:147], v[192:195], v[34:37]
	v_mfma_f32_16x16x32_bf16 v[62:65], v[140:143], v[172:175], v[62:65]
	v_mfma_f32_16x16x32_bf16 v[58:61], v[148:151], v[172:175], v[58:61]
	v_mfma_f32_16x16x32_bf16 v[54:57], v[140:143], v[180:183], v[54:57]
	v_mfma_f32_16x16x32_bf16 v[50:53], v[148:151], v[180:183], v[50:53]
	v_mfma_f32_16x16x32_bf16 v[46:49], v[140:143], v[188:191], v[46:49]
	v_mfma_f32_16x16x32_bf16 v[42:45], v[148:151], v[188:191], v[42:45]
	v_mfma_f32_16x16x32_bf16 v[38:41], v[140:143], v[196:199], v[38:41]
	v_mfma_f32_16x16x32_bf16 v[34:37], v[148:151], v[196:199], v[34:37]
	s_setprio 0
	s_setprio 1
	v_mfma_f32_16x16x32_bf16 v[30:33], v[152:155], v[168:171], v[30:33]
	v_mfma_f32_16x16x32_bf16 v[26:29], v[160:163], v[168:171], v[26:29]
	v_mfma_f32_16x16x32_bf16 v[22:25], v[152:155], v[176:179], v[22:25]
	v_mfma_f32_16x16x32_bf16 v[18:21], v[160:163], v[176:179], v[18:21]
	v_mfma_f32_16x16x32_bf16 v[12:15], v[152:155], v[184:187], v[12:15]
	v_mfma_f32_16x16x32_bf16 v[8:11], v[160:163], v[184:187], v[8:11]
	v_mfma_f32_16x16x32_bf16 v[4:7], v[152:155], v[192:195], v[4:7]
	v_mfma_f32_16x16x32_bf16 v[0:3], v[160:163], v[192:195], v[0:3]
	v_mfma_f32_16x16x32_bf16 v[30:33], v[156:159], v[172:175], v[30:33]
	v_mfma_f32_16x16x32_bf16 v[26:29], v[164:167], v[172:175], v[26:29]
	v_mfma_f32_16x16x32_bf16 v[22:25], v[156:159], v[180:183], v[22:25]
	v_mfma_f32_16x16x32_bf16 v[18:21], v[164:167], v[180:183], v[18:21]
	v_mfma_f32_16x16x32_bf16 v[12:15], v[156:159], v[188:191], v[12:15]
	v_mfma_f32_16x16x32_bf16 v[8:11], v[164:167], v[188:191], v[8:11]
	v_mfma_f32_16x16x32_bf16 v[4:7], v[156:159], v[196:199], v[4:7]
	v_mfma_f32_16x16x32_bf16 v[0:3], v[164:167], v[196:199], v[0:3]
	s_setprio 0
	s_barrier
	s_add_i32 s89, 0, 0x18000
	s_add_i32 s90, 0, 0x1c000
	v_add_u32_e32 v148, s89, v224
	v_add_u32_e32 v164, s90, v224
	ds_read_b128 v[136:139], v148
	ds_read_b128 v[140:143], v148 offset:1024
	ds_read_b128 v[144:147], v148 offset:2048
	ds_read_b128 v[148:151], v148 offset:3072
	ds_read_b128 v[152:155], v164
	ds_read_b128 v[156:159], v164 offset:1024
	ds_read_b128 v[160:163], v164 offset:2048
	ds_read_b128 v[164:167], v164 offset:3072
	s_add_u32 s46, s46, 0x80000
	s_addc_u32 s47, s47, 0
	s_mov_b32 m0, s51
	ds_read_b128 v[168:171], v226 offset:32768
	ds_read_b128 v[172:175], v226 offset:33792
	ds_read_b128 v[176:179], v226 offset:34816
	ds_read_b128 v[180:183], v226 offset:35840
	ds_read_b128 v[184:187], v226 offset:36864
	ds_read_b128 v[188:191], v226 offset:37888
	ds_read_b128 v[192:195], v226 offset:38912
	ds_read_b128 v[196:199], v226 offset:39936
	global_load_lds_dwordx4 v16, s[46:47]
	s_mov_b32 m0, s52
	s_nop 0
	global_load_lds_dwordx4 v130, s[46:47]
	s_waitcnt vmcnt(8)
	s_waitcnt lgkmcnt(0)
	s_barrier
	s_setprio 1
	s_waitcnt lgkmcnt(0)
	v_mfma_f32_16x16x32_bf16 v[126:129], v[136:139], v[168:171], v[126:129]
	v_mfma_f32_16x16x32_bf16 v[122:125], v[144:147], v[168:171], v[122:125]
	v_mfma_f32_16x16x32_bf16 v[118:121], v[136:139], v[176:179], v[118:121]
	v_mfma_f32_16x16x32_bf16 v[114:117], v[144:147], v[176:179], v[114:117]
	v_mfma_f32_16x16x32_bf16 v[110:113], v[136:139], v[184:187], v[110:113]
	v_mfma_f32_16x16x32_bf16 v[106:109], v[144:147], v[184:187], v[106:109]
	v_mfma_f32_16x16x32_bf16 v[102:105], v[136:139], v[192:195], v[102:105]
	v_mfma_f32_16x16x32_bf16 v[98:101], v[144:147], v[192:195], v[98:101]
	v_mfma_f32_16x16x32_bf16 v[126:129], v[140:143], v[172:175], v[126:129]
	v_mfma_f32_16x16x32_bf16 v[122:125], v[148:151], v[172:175], v[122:125]
	v_mfma_f32_16x16x32_bf16 v[118:121], v[140:143], v[180:183], v[118:121]
	v_mfma_f32_16x16x32_bf16 v[114:117], v[148:151], v[180:183], v[114:117]
	v_mfma_f32_16x16x32_bf16 v[110:113], v[140:143], v[188:191], v[110:113]
	v_mfma_f32_16x16x32_bf16 v[106:109], v[148:151], v[188:191], v[106:109]
	v_mfma_f32_16x16x32_bf16 v[102:105], v[140:143], v[196:199], v[102:105]
	v_mfma_f32_16x16x32_bf16 v[98:101], v[148:151], v[196:199], v[98:101]
	s_setprio 0
	s_setprio 1
	v_mfma_f32_16x16x32_bf16 v[94:97], v[152:155], v[168:171], v[94:97]
	v_mfma_f32_16x16x32_bf16 v[90:93], v[160:163], v[168:171], v[90:93]
	v_mfma_f32_16x16x32_bf16 v[86:89], v[152:155], v[176:179], v[86:89]
	v_mfma_f32_16x16x32_bf16 v[82:85], v[160:163], v[176:179], v[82:85]
	v_mfma_f32_16x16x32_bf16 v[78:81], v[152:155], v[184:187], v[78:81]
	v_mfma_f32_16x16x32_bf16 v[74:77], v[160:163], v[184:187], v[74:77]
	v_mfma_f32_16x16x32_bf16 v[70:73], v[152:155], v[192:195], v[70:73]
	v_mfma_f32_16x16x32_bf16 v[66:69], v[160:163], v[192:195], v[66:69]
	v_mfma_f32_16x16x32_bf16 v[94:97], v[156:159], v[172:175], v[94:97]
	v_mfma_f32_16x16x32_bf16 v[90:93], v[164:167], v[172:175], v[90:93]
	v_mfma_f32_16x16x32_bf16 v[86:89], v[156:159], v[180:183], v[86:89]
	v_mfma_f32_16x16x32_bf16 v[82:85], v[164:167], v[180:183], v[82:85]
	v_mfma_f32_16x16x32_bf16 v[78:81], v[156:159], v[188:191], v[78:81]
	v_mfma_f32_16x16x32_bf16 v[74:77], v[164:167], v[188:191], v[74:77]
	v_mfma_f32_16x16x32_bf16 v[70:73], v[156:159], v[196:199], v[70:73]
	v_mfma_f32_16x16x32_bf16 v[66:69], v[164:167], v[196:199], v[66:69]
	s_setprio 0
	s_barrier
	s_add_i32 s46, s89, s37
	s_add_u32 s28, s28, 0x80
	s_addc_u32 s29, s29, 0
	s_mov_b32 m0, s46
	ds_read_b128 v[168:171], v226 offset:49152
	ds_read_b128 v[172:175], v226 offset:50176
	ds_read_b128 v[176:179], v226 offset:51200
	ds_read_b128 v[180:183], v226 offset:52224
	ds_read_b128 v[184:187], v226 offset:53248
	ds_read_b128 v[188:191], v226 offset:54272
	ds_read_b128 v[192:195], v226 offset:55296
	ds_read_b128 v[196:199], v226 offset:56320
	global_load_lds_dwordx4 v16, s[28:29]
	s_add_i32 m0, s46, 0x2000
	s_add_i32 s46, s90, s37
	global_load_lds_dwordx4 v130, s[28:29]
	s_add_u32 s28, s28, 0x80000
	s_addc_u32 s29, s29, 0
	s_mov_b32 m0, s46
	s_nop 0
	global_load_lds_dwordx4 v16, s[28:29]
	s_add_i32 m0, s46, 0x2000
	s_nop 0
	global_load_lds_dwordx4 v130, s[28:29]
	v_lshl_add_u64 v[200:201], v[204:205], 0, s[34:35]
	s_mov_b32 m0, s53
	s_nop 0
	global_load_lds_dwordx4 v[200:201], off
	v_lshl_add_u64 v[200:201], v[206:207], 0, s[34:35]
	s_mov_b32 m0, s58
	s_nop 0
	global_load_lds_dwordx4 v[200:201], off
	s_waitcnt vmcnt(8)
	s_waitcnt lgkmcnt(0)
	s_barrier
	s_setprio 1
	s_waitcnt lgkmcnt(0)
	v_mfma_f32_16x16x32_bf16 v[62:65], v[136:139], v[168:171], v[62:65]
	v_mfma_f32_16x16x32_bf16 v[58:61], v[144:147], v[168:171], v[58:61]
	v_mfma_f32_16x16x32_bf16 v[54:57], v[136:139], v[176:179], v[54:57]
	v_mfma_f32_16x16x32_bf16 v[50:53], v[144:147], v[176:179], v[50:53]
	v_mfma_f32_16x16x32_bf16 v[46:49], v[136:139], v[184:187], v[46:49]
	v_mfma_f32_16x16x32_bf16 v[42:45], v[144:147], v[184:187], v[42:45]
	v_mfma_f32_16x16x32_bf16 v[38:41], v[136:139], v[192:195], v[38:41]
	v_mfma_f32_16x16x32_bf16 v[34:37], v[144:147], v[192:195], v[34:37]
	v_mfma_f32_16x16x32_bf16 v[62:65], v[140:143], v[172:175], v[62:65]
	v_mfma_f32_16x16x32_bf16 v[58:61], v[148:151], v[172:175], v[58:61]
	v_mfma_f32_16x16x32_bf16 v[54:57], v[140:143], v[180:183], v[54:57]
	v_mfma_f32_16x16x32_bf16 v[50:53], v[148:151], v[180:183], v[50:53]
	v_mfma_f32_16x16x32_bf16 v[46:49], v[140:143], v[188:191], v[46:49]
	v_mfma_f32_16x16x32_bf16 v[42:45], v[148:151], v[188:191], v[42:45]
	v_mfma_f32_16x16x32_bf16 v[38:41], v[140:143], v[196:199], v[38:41]
	v_mfma_f32_16x16x32_bf16 v[34:37], v[148:151], v[196:199], v[34:37]
	s_setprio 0
	s_setprio 1
	v_mfma_f32_16x16x32_bf16 v[30:33], v[152:155], v[168:171], v[30:33]
	v_mfma_f32_16x16x32_bf16 v[26:29], v[160:163], v[168:171], v[26:29]
	v_mfma_f32_16x16x32_bf16 v[22:25], v[152:155], v[176:179], v[22:25]
	v_mfma_f32_16x16x32_bf16 v[18:21], v[160:163], v[176:179], v[18:21]
	v_mfma_f32_16x16x32_bf16 v[12:15], v[152:155], v[184:187], v[12:15]
	v_mfma_f32_16x16x32_bf16 v[8:11], v[160:163], v[184:187], v[8:11]
	v_mfma_f32_16x16x32_bf16 v[4:7], v[152:155], v[192:195], v[4:7]
	v_mfma_f32_16x16x32_bf16 v[0:3], v[160:163], v[192:195], v[0:3]
	v_mfma_f32_16x16x32_bf16 v[30:33], v[156:159], v[172:175], v[30:33]
	v_mfma_f32_16x16x32_bf16 v[26:29], v[164:167], v[172:175], v[26:29]
	v_mfma_f32_16x16x32_bf16 v[22:25], v[156:159], v[180:183], v[22:25]
	v_mfma_f32_16x16x32_bf16 v[18:21], v[164:167], v[180:183], v[18:21]
	v_mfma_f32_16x16x32_bf16 v[12:15], v[156:159], v[188:191], v[12:15]
	v_mfma_f32_16x16x32_bf16 v[8:11], v[164:167], v[188:191], v[8:11]
	v_mfma_f32_16x16x32_bf16 v[4:7], v[156:159], v[196:199], v[4:7]
	v_mfma_f32_16x16x32_bf16 v[0:3], v[164:167], v[196:199], v[0:3]
	s_setprio 0
	s_barrier
	s_add_i32 s88, s88, 2
	s_add_u32 s44, s44, 0x100
	s_addc_u32 s45, s45, 0
	s_add_u32 s86, s86, 0x100
	s_addc_u32 s87, s87, 0
	s_cmp_gt_u32 s88, 29
	s_cbranch_scc0 .LBB0_717
	s_and_b64 vcc, exec, s[14:15]
	s_cbranch_vccz .LBB0_720
	s_barrier

.LBB0_787:
	s_add_u32 s28, s50, 0xfff80080
	s_addc_u32 s29, s51, -1
	s_add_i32 s94, 0, 0x10000
	s_cmp_eq_u32 s93, 28
	s_cselect_b32 s53, s43, s29
	s_cselect_b32 s52, s91, s28
	s_cselect_b32 s29, s41, s92
	s_cselect_b32 s28, vcc_lo, vcc_hi
	s_add_i32 s96, 0, 0x14000
	s_waitcnt vmcnt(0)
	v_add_u32_e32 v142, s94, v207
	v_add_u32_e32 v158, s96, v207
	ds_read_b128 v[130:133], v142
	ds_read_b128 v[134:137], v142 offset:1024
	ds_read_b128 v[138:141], v142 offset:2048
	ds_read_b128 v[142:145], v142 offset:3072
	ds_read_b128 v[146:149], v158
	ds_read_b128 v[150:153], v158 offset:1024
	ds_read_b128 v[154:157], v158 offset:2048
	ds_read_b128 v[158:161], v158 offset:3072
	s_add_i32 m0, s59, 0xc000
	ds_read_b128 v[162:165], v224
	ds_read_b128 v[166:169], v224 offset:1024
	ds_read_b128 v[170:173], v224 offset:2048
	ds_read_b128 v[174:177], v224 offset:3072
	ds_read_b128 v[178:181], v224 offset:4096
	ds_read_b128 v[182:185], v224 offset:5120
	ds_read_b128 v[196:199], v224 offset:6144
	ds_read_b128 v[200:203], v224 offset:7168
	global_load_lds_dwordx4 v192, s[50:51]
	s_add_i32 m0, s59, 0xe000
	s_nop 0
	global_load_lds_dwordx4 v194, s[50:51]
	s_waitcnt vmcnt(8)
	s_waitcnt lgkmcnt(0)
	s_barrier
	s_setprio 1
	s_waitcnt lgkmcnt(0)
	v_mfma_f32_16x16x32_bf16 v[126:129], v[130:133], v[162:165], v[126:129]
	v_mfma_f32_16x16x32_bf16 v[122:125], v[138:141], v[162:165], v[122:125]
	v_mfma_f32_16x16x32_bf16 v[114:117], v[130:133], v[170:173], v[114:117]
	v_mfma_f32_16x16x32_bf16 v[106:109], v[138:141], v[170:173], v[106:109]
	v_mfma_f32_16x16x32_bf16 v[98:101], v[130:133], v[178:181], v[98:101]
	v_mfma_f32_16x16x32_bf16 v[90:93], v[138:141], v[178:181], v[90:93]
	v_mfma_f32_16x16x32_bf16 v[82:85], v[130:133], v[196:199], v[82:85]
	v_mfma_f32_16x16x32_bf16 v[74:77], v[138:141], v[196:199], v[74:77]
	v_mfma_f32_16x16x32_bf16 v[126:129], v[134:137], v[166:169], v[126:129]
	v_mfma_f32_16x16x32_bf16 v[122:125], v[142:145], v[166:169], v[122:125]
	v_mfma_f32_16x16x32_bf16 v[114:117], v[134:137], v[174:177], v[114:117]
	v_mfma_f32_16x16x32_bf16 v[106:109], v[142:145], v[174:177], v[106:109]
	v_mfma_f32_16x16x32_bf16 v[98:101], v[134:137], v[182:185], v[98:101]
	v_mfma_f32_16x16x32_bf16 v[90:93], v[142:145], v[182:185], v[90:93]
	v_mfma_f32_16x16x32_bf16 v[82:85], v[134:137], v[200:203], v[82:85]
	v_mfma_f32_16x16x32_bf16 v[74:77], v[142:145], v[200:203], v[74:77]
	s_setprio 0
	s_setprio 1
	v_mfma_f32_16x16x32_bf16 v[118:121], v[146:149], v[162:165], v[118:121]
	v_mfma_f32_16x16x32_bf16 v[110:113], v[154:157], v[162:165], v[110:113]
	v_mfma_f32_16x16x32_bf16 v[102:105], v[146:149], v[170:173], v[102:105]
	v_mfma_f32_16x16x32_bf16 v[94:97], v[154:157], v[170:173], v[94:97]
	v_mfma_f32_16x16x32_bf16 v[86:89], v[146:149], v[178:181], v[86:89]
	v_mfma_f32_16x16x32_bf16 v[78:81], v[154:157], v[178:181], v[78:81]
	v_mfma_f32_16x16x32_bf16 v[70:73], v[146:149], v[196:199], v[70:73]
	v_mfma_f32_16x16x32_bf16 v[66:69], v[154:157], v[196:199], v[66:69]
	v_mfma_f32_16x16x32_bf16 v[118:121], v[150:153], v[166:169], v[118:121]
	v_mfma_f32_16x16x32_bf16 v[110:113], v[158:161], v[166:169], v[110:113]
	v_mfma_f32_16x16x32_bf16 v[102:105], v[150:153], v[174:177], v[102:105]
	v_mfma_f32_16x16x32_bf16 v[94:97], v[158:161], v[174:177], v[94:97]
	v_mfma_f32_16x16x32_bf16 v[86:89], v[150:153], v[182:185], v[86:89]
	v_mfma_f32_16x16x32_bf16 v[78:81], v[158:161], v[182:185], v[78:81]
	v_mfma_f32_16x16x32_bf16 v[70:73], v[150:153], v[200:203], v[70:73]
	v_mfma_f32_16x16x32_bf16 v[66:69], v[158:161], v[200:203], v[66:69]
	s_setprio 0
	s_barrier
	s_add_i32 s94, s94, s37
	s_mov_b32 m0, s94
	ds_read_b128 v[162:165], v224 offset:16384
	ds_read_b128 v[166:169], v224 offset:17408
	ds_read_b128 v[170:173], v224 offset:18432
	ds_read_b128 v[174:177], v224 offset:19456
	ds_read_b128 v[178:181], v224 offset:20480
	ds_read_b128 v[182:185], v224 offset:21504
	ds_read_b128 v[196:199], v224 offset:22528
	ds_read_b128 v[200:203], v224 offset:23552
	global_load_lds_dwordx4 v16, s[28:29]
	s_add_i32 m0, s94, 0x2000
	s_add_u32 s94, s28, 0x80000
	s_addc_u32 s95, s29, 0
	s_add_i32 s96, s96, s37
	global_load_lds_dwordx4 v186, s[28:29]
	s_mov_b32 m0, s96
	v_lshl_add_u64 v[230:231], s[52:53], 0, v[188:189]
	global_load_lds_dwordx4 v16, s[94:95]
	s_add_i32 m0, s96, 0x2000
	s_nop 0
	global_load_lds_dwordx4 v186, s[94:95]
	v_lshl_add_u64 v[228:229], s[52:53], 0, v[190:191]
	s_mov_b32 m0, s59
	s_nop 0
	global_load_lds_dwordx4 v[228:229], off
	s_mov_b32 m0, s83
	s_nop 0
	global_load_lds_dwordx4 v[230:231], off
	s_waitcnt vmcnt(8)
	s_waitcnt lgkmcnt(0)
	s_barrier
	s_setprio 1
	s_waitcnt lgkmcnt(0)
	v_mfma_f32_16x16x32_bf16 v[62:65], v[130:133], v[162:165], v[62:65]
	v_mfma_f32_16x16x32_bf16 v[58:61], v[138:141], v[162:165], v[58:61]
	v_mfma_f32_16x16x32_bf16 v[50:53], v[130:133], v[170:173], v[50:53]
	v_mfma_f32_16x16x32_bf16 v[42:45], v[138:141], v[170:173], v[42:45]
	v_mfma_f32_16x16x32_bf16 v[34:37], v[130:133], v[178:181], v[34:37]
	v_mfma_f32_16x16x32_bf16 v[26:29], v[138:141], v[178:181], v[26:29]
	v_mfma_f32_16x16x32_bf16 v[18:21], v[130:133], v[196:199], v[18:21]
	v_mfma_f32_16x16x32_bf16 v[8:11], v[138:141], v[196:199], v[8:11]
	v_mfma_f32_16x16x32_bf16 v[62:65], v[134:137], v[166:169], v[62:65]
	v_mfma_f32_16x16x32_bf16 v[58:61], v[142:145], v[166:169], v[58:61]
	v_mfma_f32_16x16x32_bf16 v[50:53], v[134:137], v[174:177], v[50:53]
	v_mfma_f32_16x16x32_bf16 v[42:45], v[142:145], v[174:177], v[42:45]
	v_mfma_f32_16x16x32_bf16 v[34:37], v[134:137], v[182:185], v[34:37]
	v_mfma_f32_16x16x32_bf16 v[26:29], v[142:145], v[182:185], v[26:29]
	v_mfma_f32_16x16x32_bf16 v[18:21], v[134:137], v[200:203], v[18:21]
	v_mfma_f32_16x16x32_bf16 v[8:11], v[142:145], v[200:203], v[8:11]
	s_setprio 0
	s_setprio 1
	v_mfma_f32_16x16x32_bf16 v[54:57], v[146:149], v[162:165], v[54:57]
	v_mfma_f32_16x16x32_bf16 v[46:49], v[154:157], v[162:165], v[46:49]
	v_mfma_f32_16x16x32_bf16 v[38:41], v[146:149], v[170:173], v[38:41]
	v_mfma_f32_16x16x32_bf16 v[30:33], v[154:157], v[170:173], v[30:33]
	v_mfma_f32_16x16x32_bf16 v[22:25], v[146:149], v[178:181], v[22:25]
	v_mfma_f32_16x16x32_bf16 v[12:15], v[154:157], v[178:181], v[12:15]
	v_mfma_f32_16x16x32_bf16 v[4:7], v[146:149], v[196:199], v[4:7]
	v_mfma_f32_16x16x32_bf16 v[0:3], v[154:157], v[196:199], v[0:3]
	v_mfma_f32_16x16x32_bf16 v[54:57], v[150:153], v[166:169], v[54:57]
	v_mfma_f32_16x16x32_bf16 v[46:49], v[158:161], v[166:169], v[46:49]
	v_mfma_f32_16x16x32_bf16 v[38:41], v[150:153], v[174:177], v[38:41]
	v_mfma_f32_16x16x32_bf16 v[30:33], v[158:161], v[174:177], v[30:33]
	v_mfma_f32_16x16x32_bf16 v[22:25], v[150:153], v[182:185], v[22:25]
	v_mfma_f32_16x16x32_bf16 v[12:15], v[158:161], v[182:185], v[12:15]
	v_mfma_f32_16x16x32_bf16 v[4:7], v[150:153], v[200:203], v[4:7]
	v_mfma_f32_16x16x32_bf16 v[0:3], v[158:161], v[200:203], v[0:3]
	s_setprio 0
	s_barrier
	s_add_i32 s94, 0, 0x18000
	s_add_i32 s95, 0, 0x1c000
	v_add_u32_e32 v142, s94, v207
	v_add_u32_e32 v158, s95, v207
	ds_read_b128 v[130:133], v142
	ds_read_b128 v[134:137], v142 offset:1024
	ds_read_b128 v[138:141], v142 offset:2048
	ds_read_b128 v[142:145], v142 offset:3072
	ds_read_b128 v[146:149], v158
	ds_read_b128 v[150:153], v158 offset:1024
	ds_read_b128 v[154:157], v158 offset:2048
	ds_read_b128 v[158:161], v158 offset:3072
	s_add_u32 s52, s52, 0x80000
	s_addc_u32 s53, s53, 0
	s_mov_b32 m0, s84
	ds_read_b128 v[162:165], v224 offset:32768
	ds_read_b128 v[166:169], v224 offset:33792
	ds_read_b128 v[170:173], v224 offset:34816
	ds_read_b128 v[174:177], v224 offset:35840
	ds_read_b128 v[178:181], v224 offset:36864
	ds_read_b128 v[182:185], v224 offset:37888
	ds_read_b128 v[196:199], v224 offset:38912
	ds_read_b128 v[200:203], v224 offset:39936
	global_load_lds_dwordx4 v190, s[52:53]
	s_mov_b32 m0, s85
	s_nop 0
	global_load_lds_dwordx4 v188, s[52:53]
	s_waitcnt vmcnt(8)
	s_waitcnt lgkmcnt(0)
	s_barrier
	s_setprio 1
	s_waitcnt lgkmcnt(0)
	v_mfma_f32_16x16x32_bf16 v[126:129], v[130:133], v[162:165], v[126:129]
	v_mfma_f32_16x16x32_bf16 v[122:125], v[138:141], v[162:165], v[122:125]
	v_mfma_f32_16x16x32_bf16 v[114:117], v[130:133], v[170:173], v[114:117]
	v_mfma_f32_16x16x32_bf16 v[106:109], v[138:141], v[170:173], v[106:109]
	v_mfma_f32_16x16x32_bf16 v[98:101], v[130:133], v[178:181], v[98:101]
	v_mfma_f32_16x16x32_bf16 v[90:93], v[138:141], v[178:181], v[90:93]
	v_mfma_f32_16x16x32_bf16 v[82:85], v[130:133], v[196:199], v[82:85]
	v_mfma_f32_16x16x32_bf16 v[74:77], v[138:141], v[196:199], v[74:77]
	v_mfma_f32_16x16x32_bf16 v[126:129], v[134:137], v[166:169], v[126:129]
	v_mfma_f32_16x16x32_bf16 v[122:125], v[142:145], v[166:169], v[122:125]
	v_mfma_f32_16x16x32_bf16 v[114:117], v[134:137], v[174:177], v[114:117]
	v_mfma_f32_16x16x32_bf16 v[106:109], v[142:145], v[174:177], v[106:109]
	v_mfma_f32_16x16x32_bf16 v[98:101], v[134:137], v[182:185], v[98:101]
	v_mfma_f32_16x16x32_bf16 v[90:93], v[142:145], v[182:185], v[90:93]
	v_mfma_f32_16x16x32_bf16 v[82:85], v[134:137], v[200:203], v[82:85]
	v_mfma_f32_16x16x32_bf16 v[74:77], v[142:145], v[200:203], v[74:77]
	s_setprio 0
	s_setprio 1
	v_mfma_f32_16x16x32_bf16 v[118:121], v[146:149], v[162:165], v[118:121]
	v_mfma_f32_16x16x32_bf16 v[110:113], v[154:157], v[162:165], v[110:113]
	v_mfma_f32_16x16x32_bf16 v[102:105], v[146:149], v[170:173], v[102:105]
	v_mfma_f32_16x16x32_bf16 v[94:97], v[154:157], v[170:173], v[94:97]
	v_mfma_f32_16x16x32_bf16 v[86:89], v[146:149], v[178:181], v[86:89]
	v_mfma_f32_16x16x32_bf16 v[78:81], v[154:157], v[178:181], v[78:81]
	v_mfma_f32_16x16x32_bf16 v[70:73], v[146:149], v[196:199], v[70:73]
	v_mfma_f32_16x16x32_bf16 v[66:69], v[154:157], v[196:199], v[66:69]
	v_mfma_f32_16x16x32_bf16 v[118:121], v[150:153], v[166:169], v[118:121]
	v_mfma_f32_16x16x32_bf16 v[110:113], v[158:161], v[166:169], v[110:113]
	v_mfma_f32_16x16x32_bf16 v[102:105], v[150:153], v[174:177], v[102:105]
	v_mfma_f32_16x16x32_bf16 v[94:97], v[158:161], v[174:177], v[94:97]
	v_mfma_f32_16x16x32_bf16 v[86:89], v[150:153], v[182:185], v[86:89]
	v_mfma_f32_16x16x32_bf16 v[78:81], v[158:161], v[182:185], v[78:81]
	v_mfma_f32_16x16x32_bf16 v[70:73], v[150:153], v[200:203], v[70:73]
	v_mfma_f32_16x16x32_bf16 v[66:69], v[158:161], v[200:203], v[66:69]
	s_setprio 0
	s_barrier
	s_add_i32 s52, s94, s37
	s_add_u32 s28, s28, 0x80
	s_addc_u32 s29, s29, 0
	s_mov_b32 m0, s52
	ds_read_b128 v[162:165], v224 offset:49152
	ds_read_b128 v[166:169], v224 offset:50176
	ds_read_b128 v[170:173], v224 offset:51200
	ds_read_b128 v[174:177], v224 offset:52224
	ds_read_b128 v[178:181], v224 offset:53248
	ds_read_b128 v[182:185], v224 offset:54272
	ds_read_b128 v[196:199], v224 offset:55296
	ds_read_b128 v[200:203], v224 offset:56320
	global_load_lds_dwordx4 v16, s[28:29]
	s_add_i32 m0, s52, 0x2000
	s_add_i32 s52, s95, s37
	global_load_lds_dwordx4 v186, s[28:29]
	s_add_u32 s28, s28, 0x80000
	s_addc_u32 s29, s29, 0
	s_mov_b32 m0, s52
	s_nop 0
	global_load_lds_dwordx4 v16, s[28:29]
	s_add_i32 m0, s52, 0x2000
	s_nop 0
	global_load_lds_dwordx4 v186, s[28:29]
	v_lshl_add_u64 v[204:205], v[228:229], 0, s[34:35]
	s_mov_b32 m0, s88
	s_nop 0
	global_load_lds_dwordx4 v[204:205], off
	v_lshl_add_u64 v[204:205], v[230:231], 0, s[34:35]
	s_mov_b32 m0, s89
	s_nop 0
	global_load_lds_dwordx4 v[204:205], off
	s_waitcnt vmcnt(8)
	s_waitcnt lgkmcnt(0)
	s_barrier
	s_setprio 1
	s_waitcnt lgkmcnt(0)
	v_mfma_f32_16x16x32_bf16 v[62:65], v[130:133], v[162:165], v[62:65]
	v_mfma_f32_16x16x32_bf16 v[58:61], v[138:141], v[162:165], v[58:61]
	v_mfma_f32_16x16x32_bf16 v[50:53], v[130:133], v[170:173], v[50:53]
	v_mfma_f32_16x16x32_bf16 v[42:45], v[138:141], v[170:173], v[42:45]
	v_mfma_f32_16x16x32_bf16 v[34:37], v[130:133], v[178:181], v[34:37]
	v_mfma_f32_16x16x32_bf16 v[26:29], v[138:141], v[178:181], v[26:29]
	v_mfma_f32_16x16x32_bf16 v[18:21], v[130:133], v[196:199], v[18:21]
	v_mfma_f32_16x16x32_bf16 v[8:11], v[138:141], v[196:199], v[8:11]
	v_mfma_f32_16x16x32_bf16 v[62:65], v[134:137], v[166:169], v[62:65]
	v_mfma_f32_16x16x32_bf16 v[58:61], v[142:145], v[166:169], v[58:61]
	v_mfma_f32_16x16x32_bf16 v[50:53], v[134:137], v[174:177], v[50:53]
	v_mfma_f32_16x16x32_bf16 v[42:45], v[142:145], v[174:177], v[42:45]
	v_mfma_f32_16x16x32_bf16 v[34:37], v[134:137], v[182:185], v[34:37]
	v_mfma_f32_16x16x32_bf16 v[26:29], v[142:145], v[182:185], v[26:29]
	v_mfma_f32_16x16x32_bf16 v[18:21], v[134:137], v[200:203], v[18:21]
	v_mfma_f32_16x16x32_bf16 v[8:11], v[142:145], v[200:203], v[8:11]
	s_setprio 0
	s_setprio 1
	v_mfma_f32_16x16x32_bf16 v[54:57], v[146:149], v[162:165], v[54:57]
	v_mfma_f32_16x16x32_bf16 v[46:49], v[154:157], v[162:165], v[46:49]
	v_mfma_f32_16x16x32_bf16 v[38:41], v[146:149], v[170:173], v[38:41]
	v_mfma_f32_16x16x32_bf16 v[30:33], v[154:157], v[170:173], v[30:33]
	v_mfma_f32_16x16x32_bf16 v[22:25], v[146:149], v[178:181], v[22:25]
	v_mfma_f32_16x16x32_bf16 v[12:15], v[154:157], v[178:181], v[12:15]
	v_mfma_f32_16x16x32_bf16 v[4:7], v[146:149], v[196:199], v[4:7]
	v_mfma_f32_16x16x32_bf16 v[0:3], v[154:157], v[196:199], v[0:3]
	v_mfma_f32_16x16x32_bf16 v[54:57], v[150:153], v[166:169], v[54:57]
	v_mfma_f32_16x16x32_bf16 v[46:49], v[158:161], v[166:169], v[46:49]
	v_mfma_f32_16x16x32_bf16 v[38:41], v[150:153], v[174:177], v[38:41]
	v_mfma_f32_16x16x32_bf16 v[30:33], v[158:161], v[174:177], v[30:33]
	v_mfma_f32_16x16x32_bf16 v[22:25], v[150:153], v[182:185], v[22:25]
	v_mfma_f32_16x16x32_bf16 v[12:15], v[158:161], v[182:185], v[12:15]
	v_mfma_f32_16x16x32_bf16 v[4:7], v[150:153], v[200:203], v[4:7]
	v_mfma_f32_16x16x32_bf16 v[0:3], v[158:161], v[200:203], v[0:3]
	s_setprio 0
	s_barrier
	s_add_i32 s93, s93, 2
	s_add_u32 s50, s50, 0x100
	s_addc_u32 s51, s51, 0
	s_add_u32 vcc_hi, vcc_hi, 0x100
	s_addc_u32 s92, s92, 0
	s_cmp_gt_u32 s93, 29
	s_cbranch_scc0 .LBB0_787
	s_and_b64 vcc, exec, s[22:23]
	s_cbranch_vccz .LBB0_790
	s_barrier

.LBB0_992:
	s_add_u32 s36, s26, 0x100
	s_addc_u32 s37, s27, 0
	s_add_i32 s87, 0, 0x10000
	s_cmpk_eq_i32 s86, 0x54
	s_cselect_b32 s41, s19, s37
	s_cselect_b32 s40, s18, s36
	s_cselect_b32 s29, s23, s43
	s_cselect_b32 s28, s22, s42
	s_add_i32 s88, 0, 0x14000
	v_add_u32_e32 v142, s87, v203
	v_add_u32_e32 v158, s88, v203
	ds_read_b128 v[130:133], v142
	ds_read_b128 v[134:137], v142 offset:1024
	ds_read_b128 v[138:141], v142 offset:2048
	ds_read_b128 v[142:145], v142 offset:3072
	ds_read_b128 v[146:149], v158
	ds_read_b128 v[150:153], v158 offset:1024
	ds_read_b128 v[154:157], v158 offset:2048
	ds_read_b128 v[158:161], v158 offset:3072
	s_add_i32 m0, s47, 0xc000
	ds_read_b128 v[162:165], v205
	ds_read_b128 v[166:169], v205 offset:1024
	ds_read_b128 v[170:173], v205 offset:2048
	ds_read_b128 v[174:177], v205 offset:3072
	ds_read_b128 v[178:181], v205 offset:4096
	ds_read_b128 v[192:195], v205 offset:5120
	ds_read_b128 v[196:199], v205 offset:6144
	ds_read_b128 v[224:227], v205 offset:7168
	global_load_lds_dwordx4 v188, s[26:27]
	s_add_i32 m0, s47, 0xe000
	s_nop 0
	global_load_lds_dwordx4 v190, s[26:27]
	s_waitcnt vmcnt(8)
	s_waitcnt lgkmcnt(0)
	s_barrier
	s_setprio 1
	s_waitcnt lgkmcnt(0)
	v_mfma_f32_16x16x32_bf16 v[126:129], v[130:133], v[162:165], v[126:129]
	v_mfma_f32_16x16x32_bf16 v[122:125], v[138:141], v[162:165], v[122:125]
	v_mfma_f32_16x16x32_bf16 v[114:117], v[130:133], v[170:173], v[114:117]
	v_mfma_f32_16x16x32_bf16 v[106:109], v[138:141], v[170:173], v[106:109]
	v_mfma_f32_16x16x32_bf16 v[98:101], v[130:133], v[178:181], v[98:101]
	v_mfma_f32_16x16x32_bf16 v[90:93], v[138:141], v[178:181], v[90:93]
	v_mfma_f32_16x16x32_bf16 v[82:85], v[130:133], v[196:199], v[82:85]
	v_mfma_f32_16x16x32_bf16 v[74:77], v[138:141], v[196:199], v[74:77]
	v_mfma_f32_16x16x32_bf16 v[126:129], v[134:137], v[166:169], v[126:129]
	v_mfma_f32_16x16x32_bf16 v[122:125], v[142:145], v[166:169], v[122:125]
	v_mfma_f32_16x16x32_bf16 v[114:117], v[134:137], v[174:177], v[114:117]
	v_mfma_f32_16x16x32_bf16 v[106:109], v[142:145], v[174:177], v[106:109]
	v_mfma_f32_16x16x32_bf16 v[98:101], v[134:137], v[192:195], v[98:101]
	v_mfma_f32_16x16x32_bf16 v[90:93], v[142:145], v[192:195], v[90:93]
	v_mfma_f32_16x16x32_bf16 v[82:85], v[134:137], v[224:227], v[82:85]
	v_mfma_f32_16x16x32_bf16 v[74:77], v[142:145], v[224:227], v[74:77]
	s_setprio 0
	s_setprio 1
	v_mfma_f32_16x16x32_bf16 v[118:121], v[146:149], v[162:165], v[118:121]
	v_mfma_f32_16x16x32_bf16 v[110:113], v[154:157], v[162:165], v[110:113]
	v_mfma_f32_16x16x32_bf16 v[102:105], v[146:149], v[170:173], v[102:105]
	v_mfma_f32_16x16x32_bf16 v[94:97], v[154:157], v[170:173], v[94:97]
	v_mfma_f32_16x16x32_bf16 v[86:89], v[146:149], v[178:181], v[86:89]
	v_mfma_f32_16x16x32_bf16 v[78:81], v[154:157], v[178:181], v[78:81]
	v_mfma_f32_16x16x32_bf16 v[70:73], v[146:149], v[196:199], v[70:73]
	v_mfma_f32_16x16x32_bf16 v[66:69], v[154:157], v[196:199], v[66:69]
	v_mfma_f32_16x16x32_bf16 v[118:121], v[150:153], v[166:169], v[118:121]
	v_mfma_f32_16x16x32_bf16 v[110:113], v[158:161], v[166:169], v[110:113]
	v_mfma_f32_16x16x32_bf16 v[102:105], v[150:153], v[174:177], v[102:105]
	v_mfma_f32_16x16x32_bf16 v[94:97], v[158:161], v[174:177], v[94:97]
	v_mfma_f32_16x16x32_bf16 v[86:89], v[150:153], v[192:195], v[86:89]
	v_mfma_f32_16x16x32_bf16 v[78:81], v[158:161], v[192:195], v[78:81]
	v_mfma_f32_16x16x32_bf16 v[70:73], v[150:153], v[224:227], v[70:73]
	v_mfma_f32_16x16x32_bf16 v[66:69], v[158:161], v[224:227], v[66:69]
	s_setprio 0
	s_barrier
	s_add_i32 s26, s87, s45
	v_lshl_add_u64 v[200:201], s[28:29], 0, v[16:17]
	s_mov_b32 m0, s26
	ds_read_b128 v[162:165], v205 offset:16384
	ds_read_b128 v[166:169], v205 offset:17408
	ds_read_b128 v[170:173], v205 offset:18432
	ds_read_b128 v[174:177], v205 offset:19456
	ds_read_b128 v[178:181], v205 offset:20480
	ds_read_b128 v[192:195], v205 offset:21504
	ds_read_b128 v[196:199], v205 offset:22528
	ds_read_b128 v[224:227], v205 offset:23552
	global_load_lds_dwordx4 v[200:201], off
	s_add_i32 m0, s26, 0x2000
	s_add_u32 s26, s28, 0x160000
	v_lshl_add_u64 v[206:207], s[28:29], 0, v[182:183]
	s_addc_u32 s27, s29, 0
	s_add_i32 s87, s88, s45
	global_load_lds_dwordx4 v[206:207], off
	s_mov_b32 m0, s87
	v_lshl_add_u64 v[228:229], s[40:41], 0, v[184:185]
	global_load_lds_dwordx4 v16, s[26:27]
	s_add_i32 m0, s87, 0x2000
	s_nop 0
	global_load_lds_dwordx4 v182, s[26:27]
	v_lshl_add_u64 v[216:217], s[40:41], 0, v[186:187]
	s_mov_b32 m0, s47
	s_nop 0
	global_load_lds_dwordx4 v[216:217], off
	s_mov_b32 m0, s48
	s_nop 0
	global_load_lds_dwordx4 v[228:229], off
	s_waitcnt vmcnt(8)
	s_waitcnt lgkmcnt(0)
	s_barrier
	s_setprio 1
	s_waitcnt lgkmcnt(0)
	v_mfma_f32_16x16x32_bf16 v[62:65], v[130:133], v[162:165], v[62:65]
	v_mfma_f32_16x16x32_bf16 v[58:61], v[138:141], v[162:165], v[58:61]
	v_mfma_f32_16x16x32_bf16 v[50:53], v[130:133], v[170:173], v[50:53]
	v_mfma_f32_16x16x32_bf16 v[42:45], v[138:141], v[170:173], v[42:45]
	v_mfma_f32_16x16x32_bf16 v[34:37], v[130:133], v[178:181], v[34:37]
	v_mfma_f32_16x16x32_bf16 v[26:29], v[138:141], v[178:181], v[26:29]
	v_mfma_f32_16x16x32_bf16 v[18:21], v[130:133], v[196:199], v[18:21]
	v_mfma_f32_16x16x32_bf16 v[8:11], v[138:141], v[196:199], v[8:11]
	v_mfma_f32_16x16x32_bf16 v[62:65], v[134:137], v[166:169], v[62:65]
	v_mfma_f32_16x16x32_bf16 v[58:61], v[142:145], v[166:169], v[58:61]
	v_mfma_f32_16x16x32_bf16 v[50:53], v[134:137], v[174:177], v[50:53]
	v_mfma_f32_16x16x32_bf16 v[42:45], v[142:145], v[174:177], v[42:45]
	v_mfma_f32_16x16x32_bf16 v[34:37], v[134:137], v[192:195], v[34:37]
	v_mfma_f32_16x16x32_bf16 v[26:29], v[142:145], v[192:195], v[26:29]
	v_mfma_f32_16x16x32_bf16 v[18:21], v[134:137], v[224:227], v[18:21]
	v_mfma_f32_16x16x32_bf16 v[8:11], v[142:145], v[224:227], v[8:11]
	s_setprio 0
	s_setprio 1
	v_mfma_f32_16x16x32_bf16 v[54:57], v[146:149], v[162:165], v[54:57]
	v_mfma_f32_16x16x32_bf16 v[46:49], v[154:157], v[162:165], v[46:49]
	v_mfma_f32_16x16x32_bf16 v[38:41], v[146:149], v[170:173], v[38:41]
	v_mfma_f32_16x16x32_bf16 v[30:33], v[154:157], v[170:173], v[30:33]
	v_mfma_f32_16x16x32_bf16 v[22:25], v[146:149], v[178:181], v[22:25]
	v_mfma_f32_16x16x32_bf16 v[12:15], v[154:157], v[178:181], v[12:15]
	v_mfma_f32_16x16x32_bf16 v[4:7], v[146:149], v[196:199], v[4:7]
	v_mfma_f32_16x16x32_bf16 v[0:3], v[154:157], v[196:199], v[0:3]
	v_mfma_f32_16x16x32_bf16 v[54:57], v[150:153], v[166:169], v[54:57]
	v_mfma_f32_16x16x32_bf16 v[46:49], v[158:161], v[166:169], v[46:49]
	v_mfma_f32_16x16x32_bf16 v[38:41], v[150:153], v[174:177], v[38:41]
	v_mfma_f32_16x16x32_bf16 v[30:33], v[158:161], v[174:177], v[30:33]
	v_mfma_f32_16x16x32_bf16 v[22:25], v[150:153], v[192:195], v[22:25]
	v_mfma_f32_16x16x32_bf16 v[12:15], v[158:161], v[192:195], v[12:15]
	v_mfma_f32_16x16x32_bf16 v[4:7], v[150:153], v[224:227], v[4:7]
	v_mfma_f32_16x16x32_bf16 v[0:3], v[158:161], v[224:227], v[0:3]
	s_setprio 0
	s_barrier
	s_add_i32 s87, 0, 0x18000
	s_add_i32 s88, 0, 0x1c000
	v_add_u32_e32 v142, s87, v203
	v_add_u32_e32 v158, s88, v203
	ds_read_b128 v[130:133], v142
	ds_read_b128 v[134:137], v142 offset:1024
	ds_read_b128 v[138:141], v142 offset:2048
	ds_read_b128 v[142:145], v142 offset:3072
	ds_read_b128 v[146:149], v158
	ds_read_b128 v[150:153], v158 offset:1024
	ds_read_b128 v[154:157], v158 offset:2048
	ds_read_b128 v[158:161], v158 offset:3072
	s_add_u32 s26, s40, 0x160000
	s_addc_u32 s27, s41, 0
	s_mov_b32 m0, s49
	ds_read_b128 v[162:165], v205 offset:32768
	ds_read_b128 v[166:169], v205 offset:33792
	ds_read_b128 v[170:173], v205 offset:34816
	ds_read_b128 v[174:177], v205 offset:35840
	ds_read_b128 v[178:181], v205 offset:36864
	ds_read_b128 v[192:195], v205 offset:37888
	ds_read_b128 v[196:199], v205 offset:38912
	ds_read_b128 v[224:227], v205 offset:39936
	global_load_lds_dwordx4 v186, s[26:27]
	s_mov_b32 m0, s50
	s_nop 0
	global_load_lds_dwordx4 v184, s[26:27]
	s_waitcnt vmcnt(8)
	s_waitcnt lgkmcnt(0)
	s_barrier
	s_setprio 1
	s_waitcnt lgkmcnt(0)
	v_mfma_f32_16x16x32_bf16 v[126:129], v[130:133], v[162:165], v[126:129]
	v_mfma_f32_16x16x32_bf16 v[122:125], v[138:141], v[162:165], v[122:125]
	v_mfma_f32_16x16x32_bf16 v[114:117], v[130:133], v[170:173], v[114:117]
	v_mfma_f32_16x16x32_bf16 v[106:109], v[138:141], v[170:173], v[106:109]
	v_mfma_f32_16x16x32_bf16 v[98:101], v[130:133], v[178:181], v[98:101]
	v_mfma_f32_16x16x32_bf16 v[90:93], v[138:141], v[178:181], v[90:93]
	v_mfma_f32_16x16x32_bf16 v[82:85], v[130:133], v[196:199], v[82:85]
	v_mfma_f32_16x16x32_bf16 v[74:77], v[138:141], v[196:199], v[74:77]
	v_mfma_f32_16x16x32_bf16 v[126:129], v[134:137], v[166:169], v[126:129]
	v_mfma_f32_16x16x32_bf16 v[122:125], v[142:145], v[166:169], v[122:125]
	v_mfma_f32_16x16x32_bf16 v[114:117], v[134:137], v[174:177], v[114:117]
	v_mfma_f32_16x16x32_bf16 v[106:109], v[142:145], v[174:177], v[106:109]
	v_mfma_f32_16x16x32_bf16 v[98:101], v[134:137], v[192:195], v[98:101]
	v_mfma_f32_16x16x32_bf16 v[90:93], v[142:145], v[192:195], v[90:93]
	v_mfma_f32_16x16x32_bf16 v[82:85], v[134:137], v[224:227], v[82:85]
	v_mfma_f32_16x16x32_bf16 v[74:77], v[142:145], v[224:227], v[74:77]
	s_setprio 0
	s_setprio 1
	v_mfma_f32_16x16x32_bf16 v[118:121], v[146:149], v[162:165], v[118:121]
	v_mfma_f32_16x16x32_bf16 v[110:113], v[154:157], v[162:165], v[110:113]
	v_mfma_f32_16x16x32_bf16 v[102:105], v[146:149], v[170:173], v[102:105]
	v_mfma_f32_16x16x32_bf16 v[94:97], v[154:157], v[170:173], v[94:97]
	v_mfma_f32_16x16x32_bf16 v[86:89], v[146:149], v[178:181], v[86:89]
	v_mfma_f32_16x16x32_bf16 v[78:81], v[154:157], v[178:181], v[78:81]
	v_mfma_f32_16x16x32_bf16 v[70:73], v[146:149], v[196:199], v[70:73]
	v_mfma_f32_16x16x32_bf16 v[66:69], v[154:157], v[196:199], v[66:69]
	v_mfma_f32_16x16x32_bf16 v[118:121], v[150:153], v[166:169], v[118:121]
	v_mfma_f32_16x16x32_bf16 v[110:113], v[158:161], v[166:169], v[110:113]
	v_mfma_f32_16x16x32_bf16 v[102:105], v[150:153], v[174:177], v[102:105]
	v_mfma_f32_16x16x32_bf16 v[94:97], v[158:161], v[174:177], v[94:97]
	v_mfma_f32_16x16x32_bf16 v[86:89], v[150:153], v[192:195], v[86:89]
	v_mfma_f32_16x16x32_bf16 v[78:81], v[158:161], v[192:195], v[78:81]
	v_mfma_f32_16x16x32_bf16 v[70:73], v[150:153], v[224:227], v[70:73]
	v_mfma_f32_16x16x32_bf16 v[66:69], v[158:161], v[224:227], v[66:69]
	s_setprio 0
	s_barrier
	s_add_i32 s26, s87, s45
	v_lshl_add_u64 v[200:201], v[200:201], 0, s[34:35]
	s_mov_b32 m0, s26
	ds_read_b128 v[162:165], v205 offset:49152
	ds_read_b128 v[166:169], v205 offset:50176
	ds_read_b128 v[170:173], v205 offset:51200
	ds_read_b128 v[174:177], v205 offset:52224
	ds_read_b128 v[178:181], v205 offset:53248
	ds_read_b128 v[192:195], v205 offset:54272
	ds_read_b128 v[196:199], v205 offset:55296
	ds_read_b128 v[224:227], v205 offset:56320
	global_load_lds_dwordx4 v[200:201], off
	s_add_i32 m0, s26, 0x2000
	s_add_u32 s26, s28, 0x160080
	v_lshl_add_u64 v[200:201], v[206:207], 0, s[34:35]
	s_addc_u32 s27, s29, 0
	s_add_i32 s28, s88, s45
	global_load_lds_dwordx4 v[200:201], off
	s_mov_b32 m0, s28
	s_nop 0
	global_load_lds_dwordx4 v16, s[26:27]
	s_add_i32 m0, s28, 0x2000
	s_nop 0
	global_load_lds_dwordx4 v182, s[26:27]
	v_lshl_add_u64 v[200:201], v[216:217], 0, s[34:35]
	s_mov_b32 m0, s53
	s_nop 0
	global_load_lds_dwordx4 v[200:201], off
	v_lshl_add_u64 v[200:201], v[228:229], 0, s[34:35]
	s_mov_b32 m0, s57
	s_nop 0
	global_load_lds_dwordx4 v[200:201], off
	s_waitcnt vmcnt(8)
	s_waitcnt lgkmcnt(0)
	s_barrier
	s_setprio 1
	s_waitcnt lgkmcnt(0)
	v_mfma_f32_16x16x32_bf16 v[62:65], v[130:133], v[162:165], v[62:65]
	v_mfma_f32_16x16x32_bf16 v[58:61], v[138:141], v[162:165], v[58:61]
	v_mfma_f32_16x16x32_bf16 v[50:53], v[130:133], v[170:173], v[50:53]
	v_mfma_f32_16x16x32_bf16 v[42:45], v[138:141], v[170:173], v[42:45]
	v_mfma_f32_16x16x32_bf16 v[34:37], v[130:133], v[178:181], v[34:37]
	v_mfma_f32_16x16x32_bf16 v[26:29], v[138:141], v[178:181], v[26:29]
	v_mfma_f32_16x16x32_bf16 v[18:21], v[130:133], v[196:199], v[18:21]
	v_mfma_f32_16x16x32_bf16 v[8:11], v[138:141], v[196:199], v[8:11]
	v_mfma_f32_16x16x32_bf16 v[62:65], v[134:137], v[166:169], v[62:65]
	v_mfma_f32_16x16x32_bf16 v[58:61], v[142:145], v[166:169], v[58:61]
	v_mfma_f32_16x16x32_bf16 v[50:53], v[134:137], v[174:177], v[50:53]
	v_mfma_f32_16x16x32_bf16 v[42:45], v[142:145], v[174:177], v[42:45]
	v_mfma_f32_16x16x32_bf16 v[34:37], v[134:137], v[192:195], v[34:37]
	v_mfma_f32_16x16x32_bf16 v[26:29], v[142:145], v[192:195], v[26:29]
	v_mfma_f32_16x16x32_bf16 v[18:21], v[134:137], v[224:227], v[18:21]
	v_mfma_f32_16x16x32_bf16 v[8:11], v[142:145], v[224:227], v[8:11]
	s_setprio 0
	s_setprio 1
	v_mfma_f32_16x16x32_bf16 v[54:57], v[146:149], v[162:165], v[54:57]
	v_mfma_f32_16x16x32_bf16 v[46:49], v[154:157], v[162:165], v[46:49]
	v_mfma_f32_16x16x32_bf16 v[38:41], v[146:149], v[170:173], v[38:41]
	v_mfma_f32_16x16x32_bf16 v[30:33], v[154:157], v[170:173], v[30:33]
	v_mfma_f32_16x16x32_bf16 v[22:25], v[146:149], v[178:181], v[22:25]
	v_mfma_f32_16x16x32_bf16 v[12:15], v[154:157], v[178:181], v[12:15]
	v_mfma_f32_16x16x32_bf16 v[4:7], v[146:149], v[196:199], v[4:7]
	v_mfma_f32_16x16x32_bf16 v[0:3], v[154:157], v[196:199], v[0:3]
	v_mfma_f32_16x16x32_bf16 v[54:57], v[150:153], v[166:169], v[54:57]
	v_mfma_f32_16x16x32_bf16 v[46:49], v[158:161], v[166:169], v[46:49]
	v_mfma_f32_16x16x32_bf16 v[38:41], v[150:153], v[174:177], v[38:41]
	v_mfma_f32_16x16x32_bf16 v[30:33], v[158:161], v[174:177], v[30:33]
	v_mfma_f32_16x16x32_bf16 v[22:25], v[150:153], v[192:195], v[22:25]
	v_mfma_f32_16x16x32_bf16 v[12:15], v[158:161], v[192:195], v[12:15]
	v_mfma_f32_16x16x32_bf16 v[4:7], v[150:153], v[224:227], v[4:7]
	v_mfma_f32_16x16x32_bf16 v[0:3], v[158:161], v[224:227], v[0:3]
	s_setprio 0
	s_barrier
	s_add_i32 s86, s86, 2
	s_add_u32 s42, s42, 0x100
	s_addc_u32 s43, s43, 0
	s_cmpk_gt_u32 s86, 0x55
	s_mov_b64 s[26:27], s[36:37]
	s_cbranch_scc0 .LBB0_992
	s_and_b64 vcc, exec, s[14:15]
	s_cbranch_vccz .LBB0_995
	s_barrier
